# hot loop headers (six GEMM K-loops, attention steady loops) aligned to 64 bytes; P6 epilogue loads hoisted
# speedup vs baseline: 1.0006x; 1.0006x over previous
;     __host__ __device__ bool next(int i, Unit& u) const { return i < cnt ? so.next(base + i, u) : false; }
;     __host__ __device__ bool next(int i, Unit& u) const { const int L = i * G + c; if (L >= 32) return false; u.g = L >> 3; u.pm = L & 7; u.pn = 0; return true; }
;   __device__ __forceinline__ bool next(int i,AttnUnit&u)const{ if(i>=4)return false; const int s=vcu&7; u.bh=vcu>>3; u.qb=(i==0)?s:(i==1)?15-s:(i==2)?16+s:31-s; return true; }
; template <class Epi, class Sched, bool ALIGN_EPI = false, bool SP2 = false>
; __device__ __forceinline__ void gemm_phase(PG8_LAS unsigned char* lds, const Gemm g, const Sched& S, const Epi& E) {
;     ...
;         const bool has_next = S.next(ui + 1, nxt);
;         const char* nA = has_next ? (const char*)(g.A + (size_t)nxt.g * g.gsA) + (size_t)nxt.pm * tstepA : cA; const char* nB = has_next ? (const char*)(g.Bt + (size_t)nxt.g * g.gsB) + (size_t)nxt.pn * tstepB : cB;
;         for (int t = 0; t < nt; t += 2) {
;             if constexpr (Epi::MIDK) { if (t == (nt >> 1)) { asm volatile("s_waitcnt vmcnt(0)" ::: "memory"); E.mid(acc, cur, wr, wc, fr, fq); asm volatile("s_waitcnt vmcnt(0)" ::: "memory"); } }
;             const bool last = (t == nt - 2);
;             const char* a1 = cA + (size_t)(t + 1) * kstep;
;             const char* a2 = last ? nA : cA + (size_t)(t + 2) * kstep; const char* b2 = last ? nB : cB + (size_t)(t + 2) * kstep;
;             const char* a3 = a2 + kstep; const char* b3 = b2 + kstep;
;     ...
; #pragma unroll
;         for (int a = 0; a < 2; ++a)
; #pragma unroll
;             for (int b = 0; b < 2; ++b)
; #pragma unroll
;                 for (int m = 0; m < 4; ++m)
; #pragma unroll
;                     for (int n = 0; n < 2; ++n) acc[a][b][m][n] = (f32x4){0.f, 0.f, 0.f, 0.f};
.LBB0_84:
	s_ashr_i32 s25, s24, 31
	s_lshl_b64 s[26:27], s[24:25], 20
	s_add_u32 s26, s37, s26
	s_addc_u32 s27, s38, s27
	s_ashr_i32 s23, s22, 31
	s_lshl_b64 s[28:29], s[22:23], 20
	s_add_u32 s28, s39, s28
	v_mov_b32_e32 v127, 0
	s_addc_u32 s29, s44, s29
	s_and_b64 vcc, exec, s[6:7]
	v_mov_b32_e32 v126, v127
	v_mov_b32_e32 v125, v127
	v_mov_b32_e32 v124, v127
	v_mov_b32_e32 v123, v127
	v_mov_b32_e32 v122, v127
	v_mov_b32_e32 v121, v127
	v_mov_b32_e32 v120, v127
	v_mov_b32_e32 v111, v127
	v_mov_b32_e32 v110, v127
	v_mov_b32_e32 v109, v127
	v_mov_b32_e32 v108, v127
	v_mov_b32_e32 v107, v127
	v_mov_b32_e32 v106, v127
	v_mov_b32_e32 v105, v127
	v_mov_b32_e32 v104, v127
	v_mov_b32_e32 v95, v127
	v_mov_b32_e32 v94, v127
	v_mov_b32_e32 v93, v127
	v_mov_b32_e32 v92, v127
	v_mov_b32_e32 v91, v127
	v_mov_b32_e32 v90, v127
	v_mov_b32_e32 v89, v127
	v_mov_b32_e32 v88, v127
	v_mov_b32_e32 v79, v127
	v_mov_b32_e32 v78, v127
	v_mov_b32_e32 v77, v127
	v_mov_b32_e32 v76, v127
	v_mov_b32_e32 v75, v127
	v_mov_b32_e32 v74, v127
	v_mov_b32_e32 v73, v127
	v_mov_b32_e32 v72, v127
	v_mov_b32_e32 v119, v127
	v_mov_b32_e32 v118, v127
	v_mov_b32_e32 v117, v127
	v_mov_b32_e32 v116, v127
	v_mov_b32_e32 v115, v127
	v_mov_b32_e32 v114, v127
	v_mov_b32_e32 v113, v127
	v_mov_b32_e32 v112, v127
	v_mov_b32_e32 v103, v127
	v_mov_b32_e32 v102, v127
	v_mov_b32_e32 v101, v127
	v_mov_b32_e32 v100, v127
	v_mov_b32_e32 v99, v127
	v_mov_b32_e32 v98, v127
	v_mov_b32_e32 v97, v127
	v_mov_b32_e32 v96, v127
	v_mov_b32_e32 v87, v127
	v_mov_b32_e32 v86, v127
	v_mov_b32_e32 v85, v127
	v_mov_b32_e32 v84, v127
	v_mov_b32_e32 v83, v127
	v_mov_b32_e32 v82, v127
	v_mov_b32_e32 v81, v127
	v_mov_b32_e32 v80, v127
	v_mov_b32_e32 v71, v127
	v_mov_b32_e32 v70, v127
	v_mov_b32_e32 v69, v127
	v_mov_b32_e32 v68, v127
	v_mov_b32_e32 v67, v127
	v_mov_b32_e32 v66, v127
	v_mov_b32_e32 v65, v127
	v_mov_b32_e32 v64, v127
	v_mov_b32_e32 v63, v127
	v_mov_b32_e32 v62, v127
	v_mov_b32_e32 v61, v127
	v_mov_b32_e32 v60, v127
	v_mov_b32_e32 v59, v127
	v_mov_b32_e32 v58, v127
	v_mov_b32_e32 v57, v127
	v_mov_b32_e32 v56, v127
	v_mov_b32_e32 v47, v127
	v_mov_b32_e32 v46, v127
	v_mov_b32_e32 v45, v127
	v_mov_b32_e32 v44, v127
	v_mov_b32_e32 v43, v127
	v_mov_b32_e32 v42, v127
	v_mov_b32_e32 v41, v127
	v_mov_b32_e32 v40, v127
	v_mov_b32_e32 v31, v127
	v_mov_b32_e32 v30, v127
	v_mov_b32_e32 v29, v127
	v_mov_b32_e32 v28, v127
	v_mov_b32_e32 v27, v127
	v_mov_b32_e32 v26, v127
	v_mov_b32_e32 v25, v127
	v_mov_b32_e32 v24, v127
	v_mov_b32_e32 v15, v127
	v_mov_b32_e32 v14, v127
	v_mov_b32_e32 v13, v127
	v_mov_b32_e32 v12, v127
	v_mov_b32_e32 v11, v127
	v_mov_b32_e32 v10, v127
	v_mov_b32_e32 v9, v127
	v_mov_b32_e32 v8, v127
	v_mov_b32_e32 v55, v127
	v_mov_b32_e32 v54, v127
	v_mov_b32_e32 v53, v127
	v_mov_b32_e32 v52, v127
	v_mov_b32_e32 v51, v127
	v_mov_b32_e32 v50, v127
	v_mov_b32_e32 v49, v127
	v_mov_b32_e32 v48, v127
	v_mov_b32_e32 v39, v127
	v_mov_b32_e32 v38, v127
	v_mov_b32_e32 v37, v127
	v_mov_b32_e32 v36, v127
	v_mov_b32_e32 v35, v127
	v_mov_b32_e32 v34, v127
	v_mov_b32_e32 v33, v127
	v_mov_b32_e32 v32, v127
	v_mov_b32_e32 v23, v127
	v_mov_b32_e32 v22, v127
	v_mov_b32_e32 v21, v127
	v_mov_b32_e32 v20, v127
	v_mov_b32_e32 v19, v127
	v_mov_b32_e32 v18, v127
	v_mov_b32_e32 v17, v127
	v_mov_b32_e32 v16, v127
	v_mov_b32_e32 v7, v127
	v_mov_b32_e32 v6, v127
	v_mov_b32_e32 v5, v127
	v_mov_b32_e32 v4, v127
	v_mov_b32_e32 v3, v127
	v_mov_b32_e32 v2, v127
	s_waitcnt lgkmcnt(0)
	v_mov_b32_e32 v1, v127
	v_mov_b32_e32 v0, v127
	s_cbranch_vccnz .LBB0_87
	s_and_b64 s[34:35], s[8:9], exec
	s_cselect_b32 s11, s27, s31
	s_cselect_b32 s23, s26, s30
	s_cselect_b32 s25, s29, s13
	s_cselect_b32 s40, s28, s12
	s_add_u32 s41, s12, 0x100
	s_addc_u32 s42, s13, 0
	s_add_u32 s12, s30, 0x80080
	v_mov_b32_e32 v0, 0
	s_addc_u32 s13, s31, 0
	s_mov_b32 s30, 0
	v_mov_b32_e32 v1, v0
	v_mov_b32_e32 v2, v0
	v_mov_b32_e32 v3, v0
	v_mov_b32_e32 v4, v0
	v_mov_b32_e32 v5, v0
	v_mov_b32_e32 v6, v0
	v_mov_b32_e32 v7, v0
	v_mov_b32_e32 v16, v0
	v_mov_b32_e32 v17, v0
	v_mov_b32_e32 v18, v0
	v_mov_b32_e32 v19, v0
	v_mov_b32_e32 v20, v0
	v_mov_b32_e32 v21, v0
	v_mov_b32_e32 v22, v0
	v_mov_b32_e32 v23, v0
	v_mov_b32_e32 v32, v0
	v_mov_b32_e32 v33, v0
	v_mov_b32_e32 v34, v0
	v_mov_b32_e32 v35, v0
	v_mov_b32_e32 v36, v0
	v_mov_b32_e32 v37, v0
	v_mov_b32_e32 v38, v0
	v_mov_b32_e32 v39, v0
	v_mov_b32_e32 v48, v0
	v_mov_b32_e32 v49, v0
	v_mov_b32_e32 v50, v0
	v_mov_b32_e32 v51, v0
	v_mov_b32_e32 v52, v0
	v_mov_b32_e32 v53, v0
	v_mov_b32_e32 v54, v0
	v_mov_b32_e32 v55, v0
	v_mov_b32_e32 v8, v0
	v_mov_b32_e32 v9, v0
	v_mov_b32_e32 v10, v0
	v_mov_b32_e32 v11, v0
	v_mov_b32_e32 v12, v0
	v_mov_b32_e32 v13, v0
	v_mov_b32_e32 v14, v0
	v_mov_b32_e32 v15, v0
	v_mov_b32_e32 v24, v0
	v_mov_b32_e32 v25, v0
	v_mov_b32_e32 v26, v0
	v_mov_b32_e32 v27, v0
	v_mov_b32_e32 v28, v0
	v_mov_b32_e32 v29, v0
	v_mov_b32_e32 v30, v0
	v_mov_b32_e32 v31, v0
	v_mov_b32_e32 v40, v0
	v_mov_b32_e32 v41, v0
	v_mov_b32_e32 v42, v0
	v_mov_b32_e32 v43, v0
	v_mov_b32_e32 v44, v0
	v_mov_b32_e32 v45, v0
	v_mov_b32_e32 v46, v0
	v_mov_b32_e32 v47, v0
	v_mov_b32_e32 v56, v0
	v_mov_b32_e32 v57, v0
	v_mov_b32_e32 v58, v0
	v_mov_b32_e32 v59, v0
	v_mov_b32_e32 v60, v0
	v_mov_b32_e32 v61, v0
	v_mov_b32_e32 v62, v0
	v_mov_b32_e32 v63, v0
	v_mov_b32_e32 v64, v0
	v_mov_b32_e32 v65, v0
	v_mov_b32_e32 v66, v0
	v_mov_b32_e32 v67, v0
	v_mov_b32_e32 v68, v0
	v_mov_b32_e32 v69, v0
	v_mov_b32_e32 v70, v0
	v_mov_b32_e32 v71, v0
	v_mov_b32_e32 v80, v0
	v_mov_b32_e32 v81, v0
	v_mov_b32_e32 v82, v0
	v_mov_b32_e32 v83, v0
	v_mov_b32_e32 v84, v0
	v_mov_b32_e32 v85, v0
	v_mov_b32_e32 v86, v0
	v_mov_b32_e32 v87, v0
	v_mov_b32_e32 v96, v0
	v_mov_b32_e32 v97, v0
	v_mov_b32_e32 v98, v0
	v_mov_b32_e32 v99, v0
	v_mov_b32_e32 v100, v0
	v_mov_b32_e32 v101, v0
	v_mov_b32_e32 v102, v0
	v_mov_b32_e32 v103, v0
	v_mov_b32_e32 v112, v0
	v_mov_b32_e32 v113, v0
	v_mov_b32_e32 v114, v0
	v_mov_b32_e32 v115, v0
	v_mov_b32_e32 v116, v0
	v_mov_b32_e32 v117, v0
	v_mov_b32_e32 v118, v0
	v_mov_b32_e32 v119, v0
	v_mov_b32_e32 v72, v0
	v_mov_b32_e32 v73, v0
	v_mov_b32_e32 v74, v0
	v_mov_b32_e32 v75, v0
	v_mov_b32_e32 v76, v0
	v_mov_b32_e32 v77, v0
	v_mov_b32_e32 v78, v0
	v_mov_b32_e32 v79, v0
	v_mov_b32_e32 v88, v0
	v_mov_b32_e32 v89, v0
	v_mov_b32_e32 v90, v0
	v_mov_b32_e32 v91, v0
	v_mov_b32_e32 v92, v0
	v_mov_b32_e32 v93, v0
	v_mov_b32_e32 v94, v0
	v_mov_b32_e32 v95, v0
	v_mov_b32_e32 v104, v0
	v_mov_b32_e32 v105, v0
	v_mov_b32_e32 v106, v0
	v_mov_b32_e32 v107, v0
	v_mov_b32_e32 v108, v0
	v_mov_b32_e32 v109, v0
	v_mov_b32_e32 v110, v0
	v_mov_b32_e32 v111, v0
	v_mov_b32_e32 v120, v0
	v_mov_b32_e32 v121, v0
	v_mov_b32_e32 v122, v0
	v_mov_b32_e32 v123, v0
	v_mov_b32_e32 v124, v0
	v_mov_b32_e32 v125, v0
	v_mov_b32_e32 v126, v0
	v_mov_b32_e32 v127, v0
	.p2align	6

; template <class Epi, class Sched, bool ALIGN_EPI = false, bool SP2 = false>
; __device__ __forceinline__ void gemm_phase(PG8_LAS unsigned char* lds, const Gemm g, const Sched& S, const Epi& E) {
;     ...
; #pragma unroll
;         for (int a = 0; a < 2; ++a)
; #pragma unroll
;             for (int b = 0; b < 2; ++b)
; #pragma unroll
;                 for (int m = 0; m < 4; ++m)
; #pragma unroll
;                     for (int n = 0; n < 2; ++n) acc[a][b][m][n] = (f32x4){0.f, 0.f, 0.f, 0.f};
.LBB0_252:
	s_add_i32 s55, s55, 1
	s_mul_i32 s28, s55, s33
	s_add_i32 s28, s28, s2
	s_mov_b32 s19, s64
	s_mov_b32 s30, s63
	s_and_b32 s64, s28, 7
	s_ashr_i32 s63, s28, 3
	s_cmp_lt_i32 s28, 32
	s_cselect_b64 s[34:35], -1, 0
	s_and_b64 s[28:29], s[34:35], exec
	s_cselect_b32 s30, s63, s30
	s_cselect_b32 s28, s64, s19
	s_ashr_i32 s31, s30, 31
	s_lshl_b64 s[44:45], s[30:31], 9
	s_add_u32 s19, s37, s44
	s_addc_u32 s44, s38, s45
	s_ashr_i32 s29, s28, 31
	s_lshl_b64 s[28:29], s[28:29], 19
	s_add_u32 s28, s19, s28
	s_addc_u32 s29, s44, s29
	s_lshl_b64 s[30:31], s[30:31], 17
	s_add_u32 s30, s39, s30
	v_mov_b32_e32 v127, 0
	s_addc_u32 s31, s46, s31
	s_and_b64 vcc, exec, s[4:5]
	v_mov_b32_e32 v126, v127
	v_mov_b32_e32 v125, v127
	v_mov_b32_e32 v124, v127
	v_mov_b32_e32 v123, v127
	v_mov_b32_e32 v122, v127
	v_mov_b32_e32 v121, v127
	v_mov_b32_e32 v120, v127
	v_mov_b32_e32 v111, v127
	v_mov_b32_e32 v110, v127
	v_mov_b32_e32 v109, v127
	v_mov_b32_e32 v108, v127
	v_mov_b32_e32 v107, v127
	v_mov_b32_e32 v106, v127
	v_mov_b32_e32 v105, v127
	v_mov_b32_e32 v104, v127
	v_mov_b32_e32 v95, v127
	v_mov_b32_e32 v94, v127
	v_mov_b32_e32 v93, v127
	v_mov_b32_e32 v92, v127
	v_mov_b32_e32 v91, v127
	v_mov_b32_e32 v90, v127
	v_mov_b32_e32 v89, v127
	v_mov_b32_e32 v88, v127
	v_mov_b32_e32 v79, v127
	v_mov_b32_e32 v78, v127
	v_mov_b32_e32 v77, v127
	v_mov_b32_e32 v76, v127
	v_mov_b32_e32 v75, v127
	v_mov_b32_e32 v74, v127
	v_mov_b32_e32 v73, v127
	v_mov_b32_e32 v72, v127
	v_mov_b32_e32 v119, v127
	v_mov_b32_e32 v118, v127
	v_mov_b32_e32 v117, v127
	v_mov_b32_e32 v116, v127
	v_mov_b32_e32 v115, v127
	v_mov_b32_e32 v114, v127
	v_mov_b32_e32 v113, v127
	v_mov_b32_e32 v112, v127
	v_mov_b32_e32 v103, v127
	v_mov_b32_e32 v102, v127
	v_mov_b32_e32 v101, v127
	v_mov_b32_e32 v100, v127
	v_mov_b32_e32 v99, v127
	v_mov_b32_e32 v98, v127
	v_mov_b32_e32 v97, v127
	v_mov_b32_e32 v96, v127
	v_mov_b32_e32 v87, v127
	v_mov_b32_e32 v86, v127
	v_mov_b32_e32 v85, v127
	v_mov_b32_e32 v84, v127
	v_mov_b32_e32 v83, v127
	v_mov_b32_e32 v82, v127
	v_mov_b32_e32 v81, v127
	v_mov_b32_e32 v80, v127
	v_mov_b32_e32 v71, v127
	v_mov_b32_e32 v70, v127
	v_mov_b32_e32 v69, v127
	v_mov_b32_e32 v68, v127
	v_mov_b32_e32 v67, v127
	v_mov_b32_e32 v66, v127
	v_mov_b32_e32 v65, v127
	v_mov_b32_e32 v64, v127
	v_mov_b32_e32 v63, v127
	v_mov_b32_e32 v62, v127
	v_mov_b32_e32 v61, v127
	v_mov_b32_e32 v60, v127
	v_mov_b32_e32 v59, v127
	v_mov_b32_e32 v58, v127
	v_mov_b32_e32 v57, v127
	v_mov_b32_e32 v56, v127
	v_mov_b32_e32 v47, v127
	v_mov_b32_e32 v46, v127
	v_mov_b32_e32 v45, v127
	v_mov_b32_e32 v44, v127
	v_mov_b32_e32 v43, v127
	v_mov_b32_e32 v42, v127
	v_mov_b32_e32 v41, v127
	v_mov_b32_e32 v40, v127
	v_mov_b32_e32 v31, v127
	v_mov_b32_e32 v30, v127
	v_mov_b32_e32 v29, v127
	v_mov_b32_e32 v28, v127
	v_mov_b32_e32 v27, v127
	v_mov_b32_e32 v26, v127
	v_mov_b32_e32 v25, v127
	v_mov_b32_e32 v24, v127
	v_mov_b32_e32 v15, v127
	v_mov_b32_e32 v14, v127
	v_mov_b32_e32 v13, v127
	v_mov_b32_e32 v12, v127
	v_mov_b32_e32 v11, v127
	v_mov_b32_e32 v10, v127
	v_mov_b32_e32 v9, v127
	v_mov_b32_e32 v8, v127
	v_mov_b32_e32 v55, v127
	v_mov_b32_e32 v54, v127
	v_mov_b32_e32 v53, v127
	v_mov_b32_e32 v52, v127
	v_mov_b32_e32 v51, v127
	v_mov_b32_e32 v50, v127
	v_mov_b32_e32 v49, v127
	v_mov_b32_e32 v48, v127
	v_mov_b32_e32 v39, v127
	v_mov_b32_e32 v38, v127
	v_mov_b32_e32 v37, v127
	v_mov_b32_e32 v36, v127
	v_mov_b32_e32 v35, v127
	v_mov_b32_e32 v34, v127
	v_mov_b32_e32 v33, v127
	v_mov_b32_e32 v32, v127
	v_mov_b32_e32 v23, v127
	v_mov_b32_e32 v22, v127
	v_mov_b32_e32 v21, v127
	v_mov_b32_e32 v20, v127
	v_mov_b32_e32 v19, v127
	v_mov_b32_e32 v18, v127
	v_mov_b32_e32 v17, v127
	v_mov_b32_e32 v16, v127
	v_mov_b32_e32 v7, v127
	v_mov_b32_e32 v6, v127
	v_mov_b32_e32 v5, v127
	v_mov_b32_e32 v4, v127
	v_mov_b32_e32 v3, v127
	v_mov_b32_e32 v2, v127
	v_mov_b32_e32 v1, v127
	v_mov_b32_e32 v0, v127
	s_cbranch_vccnz .LBB0_255
; template <class Epi, class Sched, bool ALIGN_EPI = false, bool SP2 = false>
; __device__ __forceinline__ void gemm_phase(PG8_LAS unsigned char* lds, const Gemm g, const Sched& S, const Epi& E) {
;     ...
;         for (int t = 0; t < nt; t += 2) {
;             if constexpr (Epi::MIDK) { if (t == (nt >> 1)) { asm volatile("s_waitcnt vmcnt(0)" ::: "memory"); E.mid(acc, cur, wr, wc, fr, fq); asm volatile("s_waitcnt vmcnt(0)" ::: "memory"); } }
;             const bool last = (t == nt - 2);
;             const char* a1 = cA + (size_t)(t + 1) * kstep;
;             const char* a2 = last ? nA : cA + (size_t)(t + 2) * kstep; const char* b2 = last ? nB : cB + (size_t)(t + 2) * kstep;
;             const char* a3 = a2 + kstep; const char* b3 = b2 + kstep;
;     ...
; #pragma unroll
;         for (int a = 0; a < 2; ++a)
; #pragma unroll
;             for (int b = 0; b < 2; ++b)
; #pragma unroll
;                 for (int m = 0; m < 4; ++m)
; #pragma unroll
;                     for (int n = 0; n < 2; ++n) acc[a][b][m][n] = (f32x4){0.f, 0.f, 0.f, 0.f};
	s_and_b64 s[44:45], s[34:35], exec
	s_cselect_b32 s19, s29, s43
	s_cselect_b32 s65, s28, s42
	s_cselect_b32 s66, s31, s41
	s_cselect_b32 s67, s30, s40
	s_add_u32 s68, s40, 0x100
	s_addc_u32 s69, s41, 0
	s_add_u32 s40, s42, 0x40080
	v_mov_b32_e32 v0, 0
	s_addc_u32 s41, s43, 0
	s_mov_b32 s42, 0
	v_mov_b32_e32 v1, v0
	v_mov_b32_e32 v2, v0
	v_mov_b32_e32 v3, v0
	v_mov_b32_e32 v4, v0
	v_mov_b32_e32 v5, v0
	v_mov_b32_e32 v6, v0
	v_mov_b32_e32 v7, v0
	v_mov_b32_e32 v16, v0
	v_mov_b32_e32 v17, v0
	v_mov_b32_e32 v18, v0
	v_mov_b32_e32 v19, v0
	v_mov_b32_e32 v20, v0
	v_mov_b32_e32 v21, v0
	v_mov_b32_e32 v22, v0
	v_mov_b32_e32 v23, v0
	v_mov_b32_e32 v32, v0
	v_mov_b32_e32 v33, v0
	v_mov_b32_e32 v34, v0
	v_mov_b32_e32 v35, v0
	v_mov_b32_e32 v36, v0
	v_mov_b32_e32 v37, v0
	v_mov_b32_e32 v38, v0
	v_mov_b32_e32 v39, v0
	v_mov_b32_e32 v48, v0
	v_mov_b32_e32 v49, v0
	v_mov_b32_e32 v50, v0
	v_mov_b32_e32 v51, v0
	v_mov_b32_e32 v52, v0
	v_mov_b32_e32 v53, v0
	v_mov_b32_e32 v54, v0
	v_mov_b32_e32 v55, v0
	v_mov_b32_e32 v8, v0
	v_mov_b32_e32 v9, v0
	v_mov_b32_e32 v10, v0
	v_mov_b32_e32 v11, v0
	v_mov_b32_e32 v12, v0
	v_mov_b32_e32 v13, v0
	v_mov_b32_e32 v14, v0
	v_mov_b32_e32 v15, v0
	v_mov_b32_e32 v24, v0
	v_mov_b32_e32 v25, v0
	v_mov_b32_e32 v26, v0
	v_mov_b32_e32 v27, v0
	v_mov_b32_e32 v28, v0
	v_mov_b32_e32 v29, v0
	v_mov_b32_e32 v30, v0
	v_mov_b32_e32 v31, v0
	v_mov_b32_e32 v40, v0
	v_mov_b32_e32 v41, v0
	v_mov_b32_e32 v42, v0
	v_mov_b32_e32 v43, v0
	v_mov_b32_e32 v44, v0
	v_mov_b32_e32 v45, v0
	v_mov_b32_e32 v46, v0
	v_mov_b32_e32 v47, v0
	v_mov_b32_e32 v56, v0
	v_mov_b32_e32 v57, v0
	v_mov_b32_e32 v58, v0
	v_mov_b32_e32 v59, v0
	v_mov_b32_e32 v60, v0
	v_mov_b32_e32 v61, v0
	v_mov_b32_e32 v62, v0
	v_mov_b32_e32 v63, v0
	v_mov_b32_e32 v64, v0
	v_mov_b32_e32 v65, v0
	v_mov_b32_e32 v66, v0
	v_mov_b32_e32 v67, v0
	v_mov_b32_e32 v68, v0
	v_mov_b32_e32 v69, v0
	v_mov_b32_e32 v70, v0
	v_mov_b32_e32 v71, v0
	v_mov_b32_e32 v80, v0
	v_mov_b32_e32 v81, v0
	v_mov_b32_e32 v82, v0
	v_mov_b32_e32 v83, v0
	v_mov_b32_e32 v84, v0
	v_mov_b32_e32 v85, v0
	v_mov_b32_e32 v86, v0
	v_mov_b32_e32 v87, v0
	v_mov_b32_e32 v96, v0
	v_mov_b32_e32 v97, v0
	v_mov_b32_e32 v98, v0
	v_mov_b32_e32 v99, v0
	v_mov_b32_e32 v100, v0
	v_mov_b32_e32 v101, v0
	v_mov_b32_e32 v102, v0
	v_mov_b32_e32 v103, v0
	v_mov_b32_e32 v112, v0
	v_mov_b32_e32 v113, v0
	v_mov_b32_e32 v114, v0
	v_mov_b32_e32 v115, v0
	v_mov_b32_e32 v116, v0
	v_mov_b32_e32 v117, v0
	v_mov_b32_e32 v118, v0
	v_mov_b32_e32 v119, v0
	v_mov_b32_e32 v72, v0
	v_mov_b32_e32 v73, v0
	v_mov_b32_e32 v74, v0
	v_mov_b32_e32 v75, v0
	v_mov_b32_e32 v76, v0
	v_mov_b32_e32 v77, v0
	v_mov_b32_e32 v78, v0
	v_mov_b32_e32 v79, v0
	v_mov_b32_e32 v88, v0
	v_mov_b32_e32 v89, v0
	v_mov_b32_e32 v90, v0
	v_mov_b32_e32 v91, v0
	v_mov_b32_e32 v92, v0
	v_mov_b32_e32 v93, v0
	v_mov_b32_e32 v94, v0
	v_mov_b32_e32 v95, v0
	v_mov_b32_e32 v104, v0
	v_mov_b32_e32 v105, v0
	v_mov_b32_e32 v106, v0
	v_mov_b32_e32 v107, v0
	v_mov_b32_e32 v108, v0
	v_mov_b32_e32 v109, v0
	v_mov_b32_e32 v110, v0
	v_mov_b32_e32 v111, v0
	v_mov_b32_e32 v120, v0
	v_mov_b32_e32 v121, v0
	v_mov_b32_e32 v122, v0
	v_mov_b32_e32 v123, v0
	v_mov_b32_e32 v124, v0
	v_mov_b32_e32 v125, v0
	v_mov_b32_e32 v126, v0
	v_mov_b32_e32 v127, v0
	.p2align	6

; #define WAIT_BAR(N) asm volatile("s_waitcnt vmcnt(" #N ") lgkmcnt(0)\n\ts_barrier":::"memory")
;   #define DMA_K(t,slot) glds16(ksrc+(long)(t)*KVBLK*DM,(unsigned)__builtin_amdgcn_readfirstlane(kdst+(slot)))
;   #define DMA_V(t,slot) do{ glds16(vsrc+(long)(t)*KVBLK*DM,(unsigned)__builtin_amdgcn_readfirstlane(vdst+2*(slot))); glds16(vsrc+64+(long)(t)*KVBLK*DM,(unsigned)__builtin_amdgcn_readfirstlane(vdst+2*(slot)+8192)); }while(0)
;   #define CMASK(P0,P1,t) do{int jb_=(t)-(NT-4); if(band&&jb_>=0)cmask(P0,P1,jb_,qrel,hi);}while(0)
;   #define START(P0,P1) do{ resc=false; \
;     { const float nm_=abase; \
;       _Pragma("unroll") for(int r=0;r<16;++r){ const float kc_=(float)((r&3)+8*(r>>2)); P0[r]=__builtin_fmaf(slope2,kc_,P0[r]+nm_); P1[r]=__builtin_fmaf(slope2,kc_+32.f,P1[r]+nm_); } } \
;     _Pragma("unroll") for(int r=0;r<16;++r)P0[r]=__builtin_amdgcn_exp2f(P0[r]); }while(0)
;   #define ROT() do{sl_prev=sl_cur;sl_cur=sl_next;sl_next=(sl_next==(NSLOT-1)*SLOTB)?0:sl_next+SLOTB;}while(0)
;   #define CMASK(P0,P1,t) do{}while(0)
;   #define CMASK(P0,P1,t) do{int jb_=(t)-(NT-4); if(band&&jb_>=0)cmask(P0,P1,jb_,qrel,hi);}while(0)
; template<int THRL> __device__ __forceinline__ void attn_unit(int hq,int hv,int qb,const bf16*Q,const bf16*__restrict__ K,const bf16*__restrict__ V,bf16*O,const float slope2,const int t0,const int ntiles,const bool band,float*Lout,const float bref,char*shm){
;     ...
;   const float dstep=64.f*slope2; const float abase=slope2*(float)(64*t0+4*hi-(q0+qrel))-bref;
;   float l_reg=0.f;f32x16 o[4];o[0]=f32x16{};o[1]=f32x16{};o[2]=f32x16{};o[3]=f32x16{};const f32x16 negm=f32x16{};
;     ...
;   bool resc=false;
;     ...
;   f32x16 pA0,pA1,pB0,pB1;
;   int sl_prev=0,sl_cur=0,sl_next=SLOTB;
;     ...
;   DMA_K(2,2*SLOTB);
;   WAIT_BAR(4);
;   qkt(pA0,pA1,Kbase,qr,negm,r32,hi);asm volatile("s_nop 15\n\ts_nop 7":"+v"(pA0),"+v"(pA1));CMASK(pA0,pA1,0);
;   START(pA0,pA1);
;   _Pragma("unroll") for(int r=0;r<16;++r)pA1[r]=__builtin_amdgcn_exp2f(pA1[r]);
;   WAIT_BAR(0);
;   DMA_K(3,0);DMA_V(1,SLOTB);
;   ROT();
;   kload8(kf,kp0+sl_cur);
;   WAIT_BAR(3);
;   s16x4 vlo[8],vhi[8]; u32x4 pw0,pw1,pw2,pw3;
;     ...
;   int t=1;
;     ...
;   for(;t+5<NT;t+=2){
.LBB0_284:
	v_lshlrev_b32_e32 v34, 1, v32
	v_and_b32_e32 v254, 32, v34
	v_lshrrev_b32_e32 v34, 2, v32
	v_and_or_b32 v34, v34, 3, v250
	v_lshlrev_b32_e32 v231, 6, v34
	v_lshl_or_b32 v34, s8, 6, v250
	v_add_u32_e32 v230, s4, v252
	v_sub_u32_e32 v34, v34, v230
	v_cvt_f32_i32_e32 v34, v34
	s_waitcnt vmcnt(0) lgkmcnt(0)
	s_barrier
	s_mov_b64 vcc, 0x60000
	s_cmp_lg_u32 0, -1
	v_fma_f32 v251, v245, v34, -s5
	v_add_f32_e32 v0, v251, v0
	v_add_f32_e32 v1, v251, v1
	v_fmac_f32_e32 v0, 0, v245
	v_add_f32_e32 v1, v245, v1
	v_exp_f32_e32 v96, v0
	v_exp_f32_e32 v97, v1
	v_lshl_add_u64 v[0:1], v[232:233], 0, vcc
	s_mov_b32 s39, m0
	s_mov_b32 m0, s16
	s_nop 0
	global_load_lds_dwordx4 v[0:1], off
	s_mov_b32 m0, s39
	s_cselect_b32 s39, 0, 0
	s_mov_b64 vcc, 0x20000
	s_add_i32 s10, s39, s10
	v_lshl_add_u64 v[0:1], v[234:235], 0, vcc
	s_add_i32 s39, s10, 0xa000
	s_mov_b32 s57, m0
	s_mov_b32 m0, s39
	s_nop 0
	global_load_lds_dwordx4 v[0:1], off
	s_mov_b32 m0, s57
	s_mov_b64 vcc, 0x20080
	v_lshl_add_u64 v[0:1], v[234:235], 0, vcc
	s_add_i32 s10, s10, 0xc000
	s_mov_b32 s39, m0
	s_mov_b32 m0, s10
	s_nop 0
	global_load_lds_dwordx4 v[0:1], off
	s_mov_b32 m0, s39
	ds_read_b128 v[204:207], v236 offset:8192
	ds_read_b128 v[196:199], v236 offset:8704
	ds_read_b128 v[200:203], v236 offset:10240
	ds_read_b128 v[188:191], v236 offset:10752
	ds_read_b128 v[192:195], v236 offset:12288
	ds_read_b128 v[180:183], v236 offset:12800
	ds_read_b128 v[184:187], v236 offset:14336
	ds_read_b128 v[176:179], v236 offset:14848
	v_add_f32_e32 v16, v251, v16
	v_add_f32_e32 v17, v251, v17
	v_add_f32_e32 v2, v251, v2
	v_add_f32_e32 v18, v251, v18
	v_add_f32_e32 v3, v251, v3
	v_add_f32_e32 v19, v251, v19
	v_add_f32_e32 v4, v251, v4
	v_add_f32_e32 v20, v251, v20
	v_add_f32_e32 v5, v251, v5
	v_add_f32_e32 v21, v251, v21
	v_add_f32_e32 v6, v251, v6
	v_add_f32_e32 v22, v251, v22
	v_add_f32_e32 v7, v251, v7
	v_add_f32_e32 v23, v251, v23
	v_add_f32_e32 v8, v251, v8
	v_add_f32_e32 v24, v251, v24
	v_add_f32_e32 v9, v251, v9
	v_add_f32_e32 v25, v251, v25
	v_add_f32_e32 v10, v251, v10
	v_add_f32_e32 v26, v251, v26
	v_add_f32_e32 v11, v251, v11
	v_add_f32_e32 v27, v251, v27
	v_add_f32_e32 v12, v251, v12
	v_add_f32_e32 v28, v251, v28
	v_add_f32_e32 v13, v251, v13
	v_add_f32_e32 v29, v251, v29
	v_add_f32_e32 v14, v251, v14
	v_add_f32_e32 v30, v251, v30
	v_add_f32_e32 v15, v251, v15
	v_add_f32_e32 v31, v251, v31
	v_fmac_f32_e32 v16, 0x42000000, v245
	v_fmac_f32_e32 v17, 0x42040000, v245
	v_fmac_f32_e32 v2, 2.0, v245
	v_fmac_f32_e32 v18, 0x42080000, v245
	v_fmac_f32_e32 v3, 0x40400000, v245
	v_fmac_f32_e32 v19, 0x420c0000, v245
	v_fmac_f32_e32 v4, 0x41000000, v245
	v_fmac_f32_e32 v20, 0x42200000, v245
	v_fmac_f32_e32 v5, 0x41100000, v245
	v_fmac_f32_e32 v21, 0x42240000, v245
	v_fmac_f32_e32 v6, 0x41200000, v245
	v_fmac_f32_e32 v22, 0x42280000, v245
	v_fmac_f32_e32 v7, 0x41300000, v245
	v_fmac_f32_e32 v23, 0x422c0000, v245
	v_fmac_f32_e32 v8, 0x41800000, v245
	v_fmac_f32_e32 v24, 0x42400000, v245
	v_fmac_f32_e32 v9, 0x41880000, v245
	v_fmac_f32_e32 v25, 0x42440000, v245
	v_fmac_f32_e32 v10, 0x41900000, v245
	v_fmac_f32_e32 v26, 0x42480000, v245
	v_fmac_f32_e32 v11, 0x41980000, v245
	v_fmac_f32_e32 v27, 0x424c0000, v245
	v_fmac_f32_e32 v12, 0x41c00000, v245
	v_fmac_f32_e32 v28, 0x42600000, v245
	v_fmac_f32_e32 v13, 0x41c80000, v245
	v_fmac_f32_e32 v29, 0x42640000, v245
	v_fmac_f32_e32 v14, 0x41d00000, v245
	v_fmac_f32_e32 v30, 0x42680000, v245
	v_fmac_f32_e32 v15, 0x41d80000, v245
	v_fmac_f32_e32 v31, 0x426c0000, v245
	v_exp_f32_e32 v98, v2
	v_exp_f32_e32 v99, v3
	v_exp_f32_e32 v100, v4
	v_exp_f32_e32 v101, v5
	v_exp_f32_e32 v102, v6
	v_exp_f32_e32 v103, v7
	v_exp_f32_e32 v104, v8
	v_exp_f32_e32 v105, v9
	v_exp_f32_e32 v106, v10
	v_exp_f32_e32 v107, v11
	v_exp_f32_e32 v108, v12
	v_exp_f32_e32 v109, v13
	v_exp_f32_e32 v110, v14
	v_exp_f32_e32 v111, v15
	v_exp_f32_e32 v80, v16
	v_exp_f32_e32 v81, v17
	v_exp_f32_e32 v82, v18
	v_exp_f32_e32 v83, v19
	v_exp_f32_e32 v84, v20
	v_exp_f32_e32 v85, v21
	v_exp_f32_e32 v86, v22
	v_exp_f32_e32 v87, v23
	v_exp_f32_e32 v88, v24
	v_exp_f32_e32 v89, v25
	v_exp_f32_e32 v90, v26
	v_exp_f32_e32 v91, v27
	v_exp_f32_e32 v92, v28
	v_exp_f32_e32 v93, v29
	v_exp_f32_e32 v94, v30
	v_exp_f32_e32 v95, v31
	s_waitcnt vmcnt(3) lgkmcnt(0)
	s_barrier
	v_add_u32_e32 v35, 0, v254
	v_writelane_b32 v255, s92, 24
	v_mov_b32_e32 v241, 0x260
	s_mov_b32 s38, 1
	v_add3_u32 v240, v35, v253, v231
	v_mul_f32_e32 v229, 0x42800000, v245
	s_mov_b32 s9, 0
	s_cmp_lt_i32 s87, 7
	s_cbranch_scc1 .LBB0_287
	s_lshl_b64 vcc, s[64:65], 8
	s_lshl_b64 s[76:77], s[76:77], 1
	s_add_u32 s76, s76, vcc_lo
	s_addc_u32 s77, s77, vcc_hi
	s_lshl_b32 s9, s88, 9
	s_and_b32 s9, s9, 0x18000
	s_lshl_b64 s[74:75], s[74:75], 1
	v_and_b32_e32 v0, 3, v32
	v_lshl_or_b32 v2, v33, 11, s9
	s_add_u32 s9, s12, s72
	v_lshlrev_b32_e32 v0, 4, v0
	v_mov_b32_e32 v1, v221
	s_addc_u32 s10, s13, s73
	v_lshl_add_u64 v[0:1], s[76:77], 0, v[0:1]
	v_mov_b32_e32 v3, v221
	s_add_u32 s72, s9, s74
	v_lshl_add_u64 v[0:1], v[0:1], 0, v[2:3]
	s_addc_u32 s73, s10, s75
	v_mov_b32_e32 v64, 0
	v_lshl_add_u64 v[208:209], s[12:13], 0, v[0:1]
	v_lshl_add_u64 v[210:211], s[72:73], 0, v[220:221]
	s_movk_i32 s57, 0x4000
	s_movk_i32 s92, 0x2000
	s_mov_b32 s39, 0
	v_mov_b32_e32 v32, 0
	v_mov_b32_e32 v33, v64
	v_mov_b32_e32 v34, v64
	v_mov_b32_e32 v35, v64
	v_mov_b32_e32 v36, v64
	v_mov_b32_e32 v37, v64
	v_mov_b32_e32 v38, v64
	v_mov_b32_e32 v39, v64
	v_mov_b32_e32 v40, v64
	v_mov_b32_e32 v41, v64
	v_mov_b32_e32 v42, v64
	v_mov_b32_e32 v43, v64
	v_mov_b32_e32 v44, v64
	v_mov_b32_e32 v45, v64
	v_mov_b32_e32 v46, v64
	v_mov_b32_e32 v47, v64
	v_mov_b32_e32 v48, 0
	v_mov_b32_e32 v49, v64
	v_mov_b32_e32 v50, v64
	v_mov_b32_e32 v51, v64
	v_mov_b32_e32 v52, v64
	v_mov_b32_e32 v53, v64
	v_mov_b32_e32 v54, v64
	v_mov_b32_e32 v55, v64
	v_mov_b32_e32 v56, v64
	v_mov_b32_e32 v57, v64
	v_mov_b32_e32 v58, v64
	v_mov_b32_e32 v59, v64
	v_mov_b32_e32 v60, v64
	v_mov_b32_e32 v61, v64
	v_mov_b32_e32 v62, v64
	v_mov_b32_e32 v63, v64
	v_mov_b32_e32 v0, 0
	v_mov_b32_e32 v1, v64
	v_mov_b32_e32 v2, v64
	v_mov_b32_e32 v3, v64
	v_mov_b32_e32 v4, v64
	v_mov_b32_e32 v5, v64
	v_mov_b32_e32 v6, v64
	v_mov_b32_e32 v7, v64
	v_mov_b32_e32 v8, v64
	v_mov_b32_e32 v9, v64
	v_mov_b32_e32 v10, v64
	v_mov_b32_e32 v11, v64
	v_mov_b32_e32 v12, v64
	v_mov_b32_e32 v13, v64
	v_mov_b32_e32 v14, v64
	v_mov_b32_e32 v15, v64
	v_mov_b32_e32 v16, 0
	v_mov_b32_e32 v17, v64
	v_mov_b32_e32 v18, v64
	v_mov_b32_e32 v19, v64
	v_mov_b32_e32 v20, v64
	v_mov_b32_e32 v21, v64
	v_mov_b32_e32 v22, v64
	v_mov_b32_e32 v23, v64
	v_mov_b32_e32 v24, v64
	v_mov_b32_e32 v25, v64
	v_mov_b32_e32 v26, v64
	v_mov_b32_e32 v27, v64
	v_mov_b32_e32 v28, v64
	v_mov_b32_e32 v29, v64
	v_mov_b32_e32 v30, v64
	v_mov_b32_e32 v31, v64
	.p2align	6

; #define WAIT_BAR(N) asm volatile("s_waitcnt vmcnt(" #N ") lgkmcnt(0)\n\ts_barrier":::"memory")
;   #define DMA_K(t,slot) glds16(ksrc+(long)(t)*KVBLK*DM,(unsigned)__builtin_amdgcn_readfirstlane(kdst+(slot)))
;   #define DMA_V(t,slot) do{ glds16(vsrc+(long)(t)*KVBLK*DM,(unsigned)__builtin_amdgcn_readfirstlane(vdst+2*(slot))); glds16(vsrc+64+(long)(t)*KVBLK*DM,(unsigned)__builtin_amdgcn_readfirstlane(vdst+2*(slot)+8192)); }while(0)
;   #define CMASK(P0,P1,t) do{int jb_=(t)-(NT-4); if(band&&jb_>=0)cmask(P0,P1,jb_,qrel,hi);}while(0)
;   #define START(P0,P1) do{ resc=false; \
;     { const float nm_=abase; \
;       _Pragma("unroll") for(int r=0;r<16;++r){ const float kc_=(float)((r&3)+8*(r>>2)); P0[r]=__builtin_fmaf(slope2,kc_,P0[r]+nm_); P1[r]=__builtin_fmaf(slope2,kc_+32.f,P1[r]+nm_); } } \
;     _Pragma("unroll") for(int r=0;r<16;++r)P0[r]=__builtin_amdgcn_exp2f(P0[r]); }while(0)
;   #define ROT() do{sl_prev=sl_cur;sl_cur=sl_next;sl_next=(sl_next==(NSLOT-1)*SLOTB)?0:sl_next+SLOTB;}while(0)
;   #define CMASK(P0,P1,t) do{}while(0)
;   #define CMASK(P0,P1,t) do{int jb_=(t)-(NT-4); if(band&&jb_>=0)cmask(P0,P1,jb_,qrel,hi);}while(0)
; template<int THRL> __device__ __forceinline__ void attn_unit(int hq,int hv,int qb,const bf16*Q,const bf16*__restrict__ K,const bf16*__restrict__ V,bf16*O,const float slope2,const int t0,const int ntiles,const bool band,float*Lout,const float bref,char*shm){
;     ...
;   const float dstep=64.f*slope2; const float abase=slope2*(float)(64*t0+4*hi-(q0+qrel))-bref;
;   float l_reg=0.f;f32x16 o[4];o[0]=f32x16{};o[1]=f32x16{};o[2]=f32x16{};o[3]=f32x16{};const f32x16 negm=f32x16{};
;     ...
;   bool resc=false;
;     ...
;   f32x16 pA0,pA1,pB0,pB1;
;   int sl_prev=0,sl_cur=0,sl_next=SLOTB;
;     ...
;   DMA_K(2,2*SLOTB);
;   WAIT_BAR(4);
;   qkt(pA0,pA1,Kbase,qr,negm,r32,hi);asm volatile("s_nop 15\n\ts_nop 7":"+v"(pA0),"+v"(pA1));CMASK(pA0,pA1,0);
;   START(pA0,pA1);
;   _Pragma("unroll") for(int r=0;r<16;++r)pA1[r]=__builtin_amdgcn_exp2f(pA1[r]);
;   WAIT_BAR(0);
;   DMA_K(3,0);DMA_V(1,SLOTB);
;   ROT();
;   kload8(kf,kp0+sl_cur);
;   WAIT_BAR(3);
;   s16x4 vlo[8],vhi[8]; u32x4 pw0,pw1,pw2,pw3;
;     ...
;   int t=1;
;     ...
;   for(;t+5<NT;t+=2){
.LBB0_334:
	v_lshlrev_b32_e32 v34, 1, v32
	v_and_b32_e32 v254, 32, v34
	v_lshrrev_b32_e32 v34, 2, v32
	v_and_or_b32 v34, v34, 3, v250
	v_lshlrev_b32_e32 v231, 6, v34
	v_lshl_or_b32 v34, s66, 6, v250
	v_add_u32_e32 v230, s4, v253
	v_sub_u32_e32 v34, v34, v230
	v_cvt_f32_i32_e32 v34, v34
	s_waitcnt vmcnt(0) lgkmcnt(0)
	s_barrier
	s_cmp_lg_u32 0, -1
	v_add_u32_e32 v35, 0, v254
	v_fma_f32 v251, v245, v34, -s5
	v_add_f32_e32 v0, v251, v0
	v_add_f32_e32 v1, v251, v1
	v_fmac_f32_e32 v0, 0, v245
	v_add_f32_e32 v1, v245, v1
	s_mov_b64 s[4:5], 0x60000
	v_exp_f32_e32 v96, v0
	v_exp_f32_e32 v97, v1
	v_lshl_add_u64 v[0:1], v[232:233], 0, s[4:5]
	s_mov_b32 s4, m0
	s_mov_b32 m0, s79
	s_nop 0
	global_load_lds_dwordx4 v[0:1], off
	s_mov_b32 m0, s4
	s_mov_b64 s[4:5], 0x20000
	v_lshl_add_u64 v[0:1], v[234:235], 0, s[4:5]
	s_cselect_b32 s4, 0, 0
	s_add_i32 s4, s4, s16
	s_add_i32 s5, s4, 0xa000
	s_mov_b32 s16, m0
	s_mov_b32 m0, s5
	s_nop 0
	global_load_lds_dwordx4 v[0:1], off
	s_mov_b32 m0, s16
	s_mov_b64 s[16:17], 0x20080
	v_lshl_add_u64 v[0:1], v[234:235], 0, s[16:17]
	s_add_i32 s4, s4, 0xc000
	s_mov_b32 s5, m0
	s_mov_b32 m0, s4
	s_nop 0
	global_load_lds_dwordx4 v[0:1], off
	s_mov_b32 m0, s5
	ds_read_b128 v[204:207], v236 offset:8192
	ds_read_b128 v[196:199], v236 offset:8704
	ds_read_b128 v[200:203], v236 offset:10240
	ds_read_b128 v[188:191], v236 offset:10752
	ds_read_b128 v[192:195], v236 offset:12288
	ds_read_b128 v[180:183], v236 offset:12800
	ds_read_b128 v[184:187], v236 offset:14336
	ds_read_b128 v[176:179], v236 offset:14848
	v_add_f32_e32 v16, v251, v16
	v_add_f32_e32 v17, v251, v17
	v_add_f32_e32 v2, v251, v2
	v_add_f32_e32 v18, v251, v18
	v_add_f32_e32 v3, v251, v3
	v_add_f32_e32 v19, v251, v19
	v_add_f32_e32 v4, v251, v4
	v_add_f32_e32 v20, v251, v20
	v_add_f32_e32 v5, v251, v5
	v_add_f32_e32 v21, v251, v21
	v_add_f32_e32 v6, v251, v6
	v_add_f32_e32 v22, v251, v22
	v_add_f32_e32 v7, v251, v7
	v_add_f32_e32 v23, v251, v23
	v_add_f32_e32 v8, v251, v8
	v_add_f32_e32 v24, v251, v24
	v_add_f32_e32 v9, v251, v9
	v_add_f32_e32 v25, v251, v25
	v_add_f32_e32 v10, v251, v10
	v_add_f32_e32 v26, v251, v26
	v_add_f32_e32 v11, v251, v11
	v_add_f32_e32 v27, v251, v27
	v_add_f32_e32 v12, v251, v12
	v_add_f32_e32 v28, v251, v28
	v_add_f32_e32 v13, v251, v13
	v_add_f32_e32 v29, v251, v29
	v_add_f32_e32 v14, v251, v14
	v_add_f32_e32 v30, v251, v30
	v_add_f32_e32 v15, v251, v15
	v_add_f32_e32 v31, v251, v31
	v_fmac_f32_e32 v16, 0x42000000, v245
	v_fmac_f32_e32 v17, 0x42040000, v245
	v_fmac_f32_e32 v2, 2.0, v245
	v_fmac_f32_e32 v18, 0x42080000, v245
	v_fmac_f32_e32 v3, 0x40400000, v245
	v_fmac_f32_e32 v19, 0x420c0000, v245
	v_fmac_f32_e32 v4, 0x41000000, v245
	v_fmac_f32_e32 v20, 0x42200000, v245
	v_fmac_f32_e32 v5, 0x41100000, v245
	v_fmac_f32_e32 v21, 0x42240000, v245
	v_fmac_f32_e32 v6, 0x41200000, v245
	v_fmac_f32_e32 v22, 0x42280000, v245
	v_fmac_f32_e32 v7, 0x41300000, v245
	v_fmac_f32_e32 v23, 0x422c0000, v245
	v_fmac_f32_e32 v8, 0x41800000, v245
	v_fmac_f32_e32 v24, 0x42400000, v245
	v_fmac_f32_e32 v9, 0x41880000, v245
	v_fmac_f32_e32 v25, 0x42440000, v245
	v_fmac_f32_e32 v10, 0x41900000, v245
	v_fmac_f32_e32 v26, 0x42480000, v245
	v_fmac_f32_e32 v11, 0x41980000, v245
	v_fmac_f32_e32 v27, 0x424c0000, v245
	v_fmac_f32_e32 v12, 0x41c00000, v245
	v_fmac_f32_e32 v28, 0x42600000, v245
	v_fmac_f32_e32 v13, 0x41c80000, v245
	v_fmac_f32_e32 v29, 0x42640000, v245
	v_fmac_f32_e32 v14, 0x41d00000, v245
	v_fmac_f32_e32 v30, 0x42680000, v245
	v_fmac_f32_e32 v15, 0x41d80000, v245
	v_fmac_f32_e32 v31, 0x426c0000, v245
	v_exp_f32_e32 v98, v2
	v_exp_f32_e32 v99, v3
	v_exp_f32_e32 v100, v4
	v_exp_f32_e32 v101, v5
	v_exp_f32_e32 v102, v6
	v_exp_f32_e32 v103, v7
	v_exp_f32_e32 v104, v8
	v_exp_f32_e32 v105, v9
	v_exp_f32_e32 v106, v10
	v_exp_f32_e32 v107, v11
	v_exp_f32_e32 v108, v12
	v_exp_f32_e32 v109, v13
	v_exp_f32_e32 v110, v14
	v_exp_f32_e32 v111, v15
	v_exp_f32_e32 v80, v16
	v_exp_f32_e32 v81, v17
	v_exp_f32_e32 v82, v18
	v_exp_f32_e32 v83, v19
	v_exp_f32_e32 v84, v20
	v_exp_f32_e32 v85, v21
	v_exp_f32_e32 v86, v22
	v_exp_f32_e32 v87, v23
	v_exp_f32_e32 v88, v24
	v_exp_f32_e32 v89, v25
	v_exp_f32_e32 v90, v26
	v_exp_f32_e32 v91, v27
	v_exp_f32_e32 v92, v28
	v_exp_f32_e32 v93, v29
	v_exp_f32_e32 v94, v30
	v_exp_f32_e32 v95, v31
	s_waitcnt vmcnt(3) lgkmcnt(0)
	s_barrier
	v_mov_b32_e32 v241, 0x260
	s_mov_b32 s38, 1
	v_add3_u32 v240, v35, v252, v231
	v_mul_f32_e32 v229, 0x42800000, v245
	s_mov_b32 s10, 0
	s_cmp_lt_i32 s89, 7
	s_cbranch_scc1 .LBB0_505
	s_lshl_b64 s[4:5], s[64:65], 8
	s_lshl_b64 s[16:17], s[74:75], 1
	v_and_b32_e32 v0, 3, v32
	s_add_u32 s4, s16, s4
	v_lshlrev_b32_e32 v0, 4, v0
	v_mov_b32_e32 v1, v221
	s_addc_u32 s5, s17, s5
	v_lshl_add_u64 v[0:1], s[4:5], 0, v[0:1]
	s_lshl_b32 s4, s78, 9
	s_and_b32 s4, s4, 0x18000
	v_lshl_or_b32 v2, v33, 11, s4
	s_lshl_b64 s[4:5], s[72:73], 1
	s_add_u32 s10, s12, s70
	s_addc_u32 s16, s13, s71
	v_mov_b32_e32 v3, v221
	s_add_u32 s4, s10, s4
	v_lshl_add_u64 v[0:1], v[0:1], 0, v[2:3]
	s_addc_u32 s5, s16, s5
	v_mov_b32_e32 v64, 0
	v_lshl_add_u64 v[208:209], s[12:13], 0, v[0:1]
	v_lshl_add_u64 v[210:211], s[4:5], 0, v[220:221]
	s_movk_i32 s5, 0x4000
	s_movk_i32 s4, 0x2000
	s_mov_b32 s17, 0
	v_mov_b32_e32 v32, 0
	v_mov_b32_e32 v33, v64
	v_mov_b32_e32 v34, v64
	v_mov_b32_e32 v35, v64
	v_mov_b32_e32 v36, v64
	v_mov_b32_e32 v37, v64
	v_mov_b32_e32 v38, v64
	v_mov_b32_e32 v39, v64
	v_mov_b32_e32 v40, v64
	v_mov_b32_e32 v41, v64
	v_mov_b32_e32 v42, v64
	v_mov_b32_e32 v43, v64
	v_mov_b32_e32 v44, v64
	v_mov_b32_e32 v45, v64
	v_mov_b32_e32 v46, v64
	v_mov_b32_e32 v47, v64
	v_mov_b32_e32 v48, 0
	v_mov_b32_e32 v49, v64
	v_mov_b32_e32 v50, v64
	v_mov_b32_e32 v51, v64
	v_mov_b32_e32 v52, v64
	v_mov_b32_e32 v53, v64
	v_mov_b32_e32 v54, v64
	v_mov_b32_e32 v55, v64
	v_mov_b32_e32 v56, v64
	v_mov_b32_e32 v57, v64
	v_mov_b32_e32 v58, v64
	v_mov_b32_e32 v59, v64
	v_mov_b32_e32 v60, v64
	v_mov_b32_e32 v61, v64
	v_mov_b32_e32 v62, v64
	v_mov_b32_e32 v63, v64
	v_mov_b32_e32 v0, 0
	v_mov_b32_e32 v1, v64
	v_mov_b32_e32 v2, v64
	v_mov_b32_e32 v3, v64
	v_mov_b32_e32 v4, v64
	v_mov_b32_e32 v5, v64
	v_mov_b32_e32 v6, v64
	v_mov_b32_e32 v7, v64
	v_mov_b32_e32 v8, v64
	v_mov_b32_e32 v9, v64
	v_mov_b32_e32 v10, v64
	v_mov_b32_e32 v11, v64
	v_mov_b32_e32 v12, v64
	v_mov_b32_e32 v13, v64
	v_mov_b32_e32 v14, v64
	v_mov_b32_e32 v15, v64
	v_mov_b32_e32 v16, 0
	v_mov_b32_e32 v17, v64
	v_mov_b32_e32 v18, v64
	v_mov_b32_e32 v19, v64
	v_mov_b32_e32 v20, v64
	v_mov_b32_e32 v21, v64
	v_mov_b32_e32 v22, v64
	v_mov_b32_e32 v23, v64
	v_mov_b32_e32 v24, v64
	v_mov_b32_e32 v25, v64
	v_mov_b32_e32 v26, v64
	v_mov_b32_e32 v27, v64
	v_mov_b32_e32 v28, v64
	v_mov_b32_e32 v29, v64
	v_mov_b32_e32 v30, v64
	v_mov_b32_e32 v31, v64
	.p2align	6

; #define RT_(aw, pw, lo) ((lo ? bf_lo(aw) : bf_hi(aw)) * __builtin_amdgcn_rcpf(fmaxf(lo ? bf_lo(pw) : bf_hi(pw), 1e-30f)))
;     __device__ __forceinline__ void mid(f32x4 (&acc)[2][2][4][2], const Unit& u, int wr, int wc, int fr, int fq) const {
;         const int col0 = u.pn * BM + wc * 32 + 8 * fq, row0 = u.pm * BM + wr * 64 + fr;
;         unsigned long long ro_ = ((unsigned long long)row0 * 2048 + col0) * 2; asm volatile("" : "+v"(ro_));
;         const bf16_t* ga = (const bf16_t*)((const char*)GA + ro_); const bf16_t* gp = (const bf16_t*)((const char*)GP + ro_);
; #pragma unroll
;         for (int ai = 0; ai < 2; ++ai)
; #pragma unroll
;             for (int m = 0; m < 4; ++m)
; #pragma unroll
;                 for (int bj = 0; bj < 2; ++bj) { const size_t o_ = (size_t)(ai * HALF + m * 16) * 2048 + bj * HALF;
;                     const u32x4 a = *(const u32x4*)(ga + o_), p = *(const u32x4*)(gp + o_);
;     ...
;                     acc[ai][bj][m][0][0] *= RT_(a.x, p.x, 1); acc[ai][bj][m][0][1] *= RT_(a.x, p.x, 0); acc[ai][bj][m][0][2] *= RT_(a.y, p.y, 1); acc[ai][bj][m][0][3] *= RT_(a.y, p.y, 0);
;                     acc[ai][bj][m][1][0] *= RT_(a.z, p.z, 1); acc[ai][bj][m][1][1] *= RT_(a.z, p.z, 0); acc[ai][bj][m][1][2] *= RT_(a.w, p.w, 1); acc[ai][bj][m][1][3] *= RT_(a.w, p.w, 0);
;     ...
;                     asm volatile("" ::: "memory"); }
;     }
.LBB0_672:
	v_mov_b64_e32 v[128:129], v[180:181]
	s_waitcnt vmcnt(0)
	s_nop 0
	v_lshl_add_u64 v[182:183], s[12:13], 0, v[128:129]
	v_lshl_add_u64 v[184:185], s[10:11], 0, v[128:129]
	flat_load_dwordx4 v[136:139], v[182:183]
	flat_load_dwordx4 v[140:143], v[184:185]
	flat_load_dwordx4 v[150:153], v[182:183] offset:256
	flat_load_dwordx4 v[154:157], v[184:185] offset:256
	v_add_co_u32_e32 v144, vcc, s56, v184
	s_waitcnt vmcnt(0) lgkmcnt(0)
	v_lshlrev_b32_e32 v158, 16, v136
	v_addc_co_u32_e32 v145, vcc, 0, v185, vcc
	v_add_co_u32_e32 v148, vcc, s56, v182
	v_and_b32_e32 v159, 0xffff0000, v136
	s_nop 0
	v_addc_co_u32_e32 v149, vcc, 0, v183, vcc
	flat_load_dwordx4 v[128:131], v[144:145]
	flat_load_dwordx4 v[132:135], v[148:149]
	v_lshlrev_b32_e32 v146, 16, v140
	v_and_b32_e32 v147, 0xffff0000, v140
	v_lshlrev_b32_e32 v177, 16, v137
	v_and_b32_e32 v179, 0xffff0000, v137
	v_lshlrev_b32_e32 v136, 16, v141
	v_and_b32_e32 v137, 0xffff0000, v141
	v_lshlrev_b32_e32 v140, 16, v142
	v_and_b32_e32 v141, 0xffff0000, v142
	v_lshlrev_b32_e32 v142, 16, v139
	v_and_b32_e32 v194, 0xffff0000, v139
	v_lshlrev_b32_e32 v192, 16, v138
	v_and_b32_e32 v193, 0xffff0000, v138
	v_lshlrev_b32_e32 v138, 16, v143
	v_and_b32_e32 v139, 0xffff0000, v143
	v_max_f32_e32 v158, v158, v158
	v_max_f32_e32 v159, v159, v159
	v_max_f32_e32 v195, v142, v142
	v_max_f32_e32 v194, v194, v194
	v_lshlrev_b32_e32 v142, 16, v154
	v_and_b32_e32 v143, 0xffff0000, v154
	v_lshlrev_b32_e32 v154, 16, v151
	v_and_b32_e32 v198, 0xffff0000, v151
	v_lshlrev_b32_e32 v196, 16, v150
	v_and_b32_e32 v197, 0xffff0000, v150
	v_lshlrev_b32_e32 v150, 16, v155
	v_and_b32_e32 v151, 0xffff0000, v155
	v_max_f32_e32 v155, 0xda24260, v158
	v_max_f32_e32 v158, 0xda24260, v159
	v_max_f32_e32 v195, 0xda24260, v195
	v_max_f32_e32 v199, 0xda24260, v194
	v_max_f32_e32 v201, v154, v154
	v_max_f32_e32 v198, v198, v198
	v_rcp_f32_e32 v154, v155
	v_rcp_f32_e32 v155, v158
	v_rcp_f32_e32 v194, v195
	v_rcp_f32_e32 v195, v199
	v_max_f32_e32 v199, 0xda24260, v201
	v_max_f32_e32 v201, 0xda24260, v198
	v_rcp_f32_e32 v198, v199
	v_rcp_f32_e32 v199, v201
	v_max_f32_e32 v177, v177, v177
	v_max_f32_e32 v179, v179, v179
	v_max_f32_e32 v192, v192, v192
	v_pk_mul_f32 v[146:147], v[154:155], v[146:147]
	v_pk_mul_f32 v[138:139], v[194:195], v[138:139]
	v_max_f32_e32 v159, 0xda24260, v177
	v_max_f32_e32 v177, 0xda24260, v179
	v_max_f32_e32 v179, 0xda24260, v192
	v_max_f32_e32 v196, v196, v196
	v_max_f32_e32 v197, v197, v197
	v_pk_mul_f32 v[124:125], v[124:125], v[146:147]
	v_pk_mul_f32 v[122:123], v[122:123], v[138:139]
	v_pk_mul_f32 v[138:139], v[198:199], v[150:151]
	flat_load_dwordx4 v[144:147], v[144:145] offset:256
	s_nop 0
	flat_load_dwordx4 v[148:151], v[148:149] offset:256
	v_rcp_f32_e32 v158, v159
	v_rcp_f32_e32 v159, v177
	v_rcp_f32_e32 v192, v179
	v_max_f32_e32 v177, 0xda24260, v196
	v_max_f32_e32 v179, 0xda24260, v197
	v_rcp_f32_e32 v196, v177
	v_rcp_f32_e32 v197, v179
	v_pk_mul_f32 v[136:137], v[158:159], v[136:137]
	v_lshlrev_b32_e32 v200, 16, v152
	v_pk_mul_f32 v[126:127], v[126:127], v[136:137]
	v_pk_mul_f32 v[136:137], v[196:197], v[142:143]
	v_pk_mul_f32 v[118:119], v[118:119], v[138:139]
	v_pk_mul_f32 v[116:117], v[116:117], v[136:137]
	v_and_b32_e32 v137, 0xffff0000, v152
	v_max_f32_e32 v136, v200, v200
	v_max_f32_e32 v137, v137, v137
	v_max_f32_e32 v136, 0xda24260, v136
	v_max_f32_e32 v137, 0xda24260, v137
	v_rcp_f32_e32 v136, v136
	v_rcp_f32_e32 v137, v137
	v_lshlrev_b32_e32 v138, 16, v156
	v_and_b32_e32 v139, 0xffff0000, v156
	v_max_f32_e32 v193, v193, v193
	v_pk_mul_f32 v[136:137], v[136:137], v[138:139]
	v_lshlrev_b32_e32 v138, 16, v153
	v_and_b32_e32 v139, 0xffff0000, v153
	v_max_f32_e32 v138, v138, v138
	v_max_f32_e32 v139, v139, v139
	v_max_f32_e32 v138, 0xda24260, v138
	v_max_f32_e32 v139, 0xda24260, v139
	v_rcp_f32_e32 v138, v138
	v_rcp_f32_e32 v139, v139
	v_pk_mul_f32 v[112:113], v[112:113], v[136:137]
	v_lshlrev_b32_e32 v136, 16, v157
	v_and_b32_e32 v137, 0xffff0000, v157
	v_pk_mul_f32 v[136:137], v[138:139], v[136:137]
	s_waitcnt vmcnt(0) lgkmcnt(0)
	v_lshlrev_b32_e32 v138, 16, v132
	v_and_b32_e32 v132, 0xffff0000, v132
	v_max_f32_e32 v193, 0xda24260, v193
	v_max_f32_e32 v138, v138, v138
	v_max_f32_e32 v132, v132, v132
	v_rcp_f32_e32 v193, v193
	v_max_f32_e32 v138, 0xda24260, v138
	v_max_f32_e32 v132, 0xda24260, v132
	v_rcp_f32_e32 v138, v138
	v_rcp_f32_e32 v139, v132
	v_add_co_u32_e32 v154, vcc, s63, v184
	v_pk_mul_f32 v[140:141], v[192:193], v[140:141]
	s_nop 0
	v_addc_co_u32_e32 v155, vcc, 0, v185, vcc
	v_pk_mul_f32 v[114:115], v[114:115], v[136:137]
	v_lshlrev_b32_e32 v136, 16, v128
	v_and_b32_e32 v137, 0xffff0000, v128
	v_add_co_u32_e32 v156, vcc, s63, v182
	v_pk_mul_f32 v[120:121], v[120:121], v[140:141]
	v_pk_mul_f32 v[152:153], v[138:139], v[136:137]
	v_addc_co_u32_e32 v157, vcc, 0, v183, vcc
	flat_load_dwordx4 v[136:139], v[154:155]
	flat_load_dwordx4 v[140:143], v[156:157]
	v_lshlrev_b32_e32 v128, 16, v133
	v_max_f32_e32 v128, v128, v128
	v_max_f32_e32 v128, 0xda24260, v128
	v_rcp_f32_e32 v132, v128
	v_and_b32_e32 v128, 0xffff0000, v133
	v_max_f32_e32 v128, v128, v128
	v_max_f32_e32 v128, 0xda24260, v128
	v_rcp_f32_e32 v133, v128
	v_lshlrev_b32_e32 v128, 16, v129
	v_and_b32_e32 v129, 0xffff0000, v129
	v_pk_mul_f32 v[128:129], v[132:133], v[128:129]
	v_lshlrev_b32_e32 v132, 16, v134
	v_and_b32_e32 v133, 0xffff0000, v134
	v_max_f32_e32 v132, v132, v132
	v_max_f32_e32 v133, v133, v133
	v_max_f32_e32 v132, 0xda24260, v132
	v_max_f32_e32 v133, 0xda24260, v133
	v_rcp_f32_e32 v132, v132
	v_rcp_f32_e32 v133, v133
	v_pk_mul_f32 v[110:111], v[110:111], v[128:129]
	v_lshlrev_b32_e32 v128, 16, v130
; #define RT_(aw, pw, lo) ((lo ? bf_lo(aw) : bf_hi(aw)) * __builtin_amdgcn_rcpf(fmaxf(lo ? bf_lo(pw) : bf_hi(pw), 1e-30f)))
;     __device__ __forceinline__ void mid(f32x4 (&acc)[2][2][4][2], const Unit& u, int wr, int wc, int fr, int fq) const {
;         const int col0 = u.pn * BM + wc * 32 + 8 * fq, row0 = u.pm * BM + wr * 64 + fr;
;         unsigned long long ro_ = ((unsigned long long)row0 * 2048 + col0) * 2; asm volatile("" : "+v"(ro_));
;         const bf16_t* ga = (const bf16_t*)((const char*)GA + ro_); const bf16_t* gp = (const bf16_t*)((const char*)GP + ro_);
; #pragma unroll
;         for (int ai = 0; ai < 2; ++ai)
; #pragma unroll
;             for (int m = 0; m < 4; ++m)
; #pragma unroll
;                 for (int bj = 0; bj < 2; ++bj) { const size_t o_ = (size_t)(ai * HALF + m * 16) * 2048 + bj * HALF;
;                     const u32x4 a = *(const u32x4*)(ga + o_), p = *(const u32x4*)(gp + o_);
;     ...
;                     acc[ai][bj][m][0][0] *= RT_(a.x, p.x, 1); acc[ai][bj][m][0][1] *= RT_(a.x, p.x, 0); acc[ai][bj][m][0][2] *= RT_(a.y, p.y, 1); acc[ai][bj][m][0][3] *= RT_(a.y, p.y, 0);
;                     acc[ai][bj][m][1][0] *= RT_(a.z, p.z, 1); acc[ai][bj][m][1][1] *= RT_(a.z, p.z, 0); acc[ai][bj][m][1][2] *= RT_(a.w, p.w, 1); acc[ai][bj][m][1][3] *= RT_(a.w, p.w, 0);
;     ...
;                     asm volatile("" ::: "memory"); }
;     }
	v_and_b32_e32 v129, 0xffff0000, v130
	v_lshlrev_b32_e32 v130, 16, v135
	v_max_f32_e32 v130, v130, v130
	v_max_f32_e32 v130, 0xda24260, v130
	v_pk_mul_f32 v[128:129], v[132:133], v[128:129]
	v_rcp_f32_e32 v132, v130
	v_and_b32_e32 v130, 0xffff0000, v135
	v_max_f32_e32 v130, v130, v130
	v_max_f32_e32 v130, 0xda24260, v130
	v_rcp_f32_e32 v133, v130
	v_pk_mul_f32 v[104:105], v[104:105], v[128:129]
	v_lshlrev_b32_e32 v128, 16, v131
	v_and_b32_e32 v129, 0xffff0000, v131
	v_lshlrev_b32_e32 v130, 16, v148
	v_and_b32_e32 v131, 0xffff0000, v148
	v_max_f32_e32 v130, v130, v130
	v_max_f32_e32 v131, v131, v131
	v_max_f32_e32 v130, 0xda24260, v130
	v_max_f32_e32 v131, 0xda24260, v131
	v_rcp_f32_e32 v130, v130
	v_rcp_f32_e32 v131, v131
	v_pk_mul_f32 v[128:129], v[132:133], v[128:129]
	v_pk_mul_f32 v[108:109], v[108:109], v[152:153]
	v_pk_mul_f32 v[106:107], v[106:107], v[128:129]
	v_lshlrev_b32_e32 v128, 16, v144
	v_and_b32_e32 v129, 0xffff0000, v144
	v_pk_mul_f32 v[128:129], v[130:131], v[128:129]
	v_lshlrev_b32_e32 v130, 16, v149
	v_and_b32_e32 v131, 0xffff0000, v149
	v_max_f32_e32 v130, v130, v130
	v_max_f32_e32 v131, v131, v131
	v_max_f32_e32 v130, 0xda24260, v130
	v_max_f32_e32 v131, 0xda24260, v131
	v_rcp_f32_e32 v130, v130
	v_rcp_f32_e32 v131, v131
	v_pk_mul_f32 v[100:101], v[100:101], v[128:129]
	v_lshlrev_b32_e32 v128, 16, v145
	v_and_b32_e32 v129, 0xffff0000, v145
	v_pk_mul_f32 v[128:129], v[130:131], v[128:129]
	v_lshlrev_b32_e32 v130, 16, v150
	v_and_b32_e32 v131, 0xffff0000, v150
	v_max_f32_e32 v130, v130, v130
	v_max_f32_e32 v131, v131, v131
	v_max_f32_e32 v130, 0xda24260, v130
	v_max_f32_e32 v131, 0xda24260, v131
	v_rcp_f32_e32 v130, v130
	v_rcp_f32_e32 v131, v131
	flat_load_dwordx4 v[132:135], v[154:155] offset:256
	s_nop 0
	flat_load_dwordx4 v[152:155], v[156:157] offset:256
	v_pk_mul_f32 v[102:103], v[102:103], v[128:129]
	v_lshlrev_b32_e32 v128, 16, v146
	v_and_b32_e32 v129, 0xffff0000, v146
	v_pk_mul_f32 v[128:129], v[130:131], v[128:129]
	v_lshlrev_b32_e32 v130, 16, v151
	v_and_b32_e32 v131, 0xffff0000, v151
	v_max_f32_e32 v130, v130, v130
	v_max_f32_e32 v131, v131, v131
	v_max_f32_e32 v130, 0xda24260, v130
	v_max_f32_e32 v131, 0xda24260, v131
	v_rcp_f32_e32 v130, v130
	v_rcp_f32_e32 v131, v131
	v_pk_mul_f32 v[96:97], v[96:97], v[128:129]
	v_lshlrev_b32_e32 v128, 16, v147
	v_and_b32_e32 v129, 0xffff0000, v147
	v_pk_mul_f32 v[128:129], v[130:131], v[128:129]
	s_waitcnt vmcnt(0) lgkmcnt(0)
	v_lshlrev_b32_e32 v130, 16, v140
	v_and_b32_e32 v131, 0xffff0000, v140
	v_max_f32_e32 v130, v130, v130
	v_max_f32_e32 v131, v131, v131
	v_max_f32_e32 v130, 0xda24260, v130
	v_max_f32_e32 v131, 0xda24260, v131
	v_rcp_f32_e32 v130, v130
	v_rcp_f32_e32 v131, v131
	v_pk_mul_f32 v[98:99], v[98:99], v[128:129]
	v_lshlrev_b32_e32 v128, 16, v136
	v_and_b32_e32 v129, 0xffff0000, v136
	v_pk_mul_f32 v[148:149], v[130:131], v[128:129]
	v_lshlrev_b32_e32 v128, 16, v141
	v_max_f32_e32 v128, v128, v128
	v_max_f32_e32 v128, 0xda24260, v128
	v_rcp_f32_e32 v140, v128
	v_and_b32_e32 v128, 0xffff0000, v141
	v_add_co_u32_e32 v150, vcc, s64, v184
	v_max_f32_e32 v128, v128, v128
	s_nop 0
	v_addc_co_u32_e32 v151, vcc, 0, v185, vcc
	v_max_f32_e32 v128, 0xda24260, v128
	v_add_co_u32_e32 v156, vcc, s64, v182
	v_rcp_f32_e32 v141, v128
	s_nop 0
	v_addc_co_u32_e32 v157, vcc, 0, v183, vcc
	flat_load_dwordx4 v[128:131], v[150:151]
	flat_load_dwordx4 v[144:147], v[156:157]
	v_lshlrev_b32_e32 v136, 16, v137
	v_and_b32_e32 v137, 0xffff0000, v137
	v_pk_mul_f32 v[136:137], v[140:141], v[136:137]
	v_lshlrev_b32_e32 v140, 16, v142
	v_and_b32_e32 v141, 0xffff0000, v142
	v_max_f32_e32 v140, v140, v140
	v_max_f32_e32 v141, v141, v141
	v_max_f32_e32 v140, 0xda24260, v140
	v_max_f32_e32 v141, 0xda24260, v141
	v_rcp_f32_e32 v140, v140
	v_rcp_f32_e32 v141, v141
	v_pk_mul_f32 v[94:95], v[94:95], v[136:137]
	v_lshlrev_b32_e32 v136, 16, v138
	v_and_b32_e32 v137, 0xffff0000, v138
	v_lshlrev_b32_e32 v138, 16, v143
	v_max_f32_e32 v138, v138, v138
	v_max_f32_e32 v138, 0xda24260, v138
	v_pk_mul_f32 v[136:137], v[140:141], v[136:137]
	v_rcp_f32_e32 v140, v138
	v_and_b32_e32 v138, 0xffff0000, v143
	v_max_f32_e32 v138, v138, v138
	v_max_f32_e32 v138, 0xda24260, v138
	v_rcp_f32_e32 v141, v138
	v_pk_mul_f32 v[88:89], v[88:89], v[136:137]
	v_lshlrev_b32_e32 v136, 16, v139
	v_and_b32_e32 v137, 0xffff0000, v139
	v_pk_mul_f32 v[92:93], v[92:93], v[148:149]
	v_pk_mul_f32 v[136:137], v[140:141], v[136:137]
	flat_load_dwordx4 v[140:143], v[150:151] offset:256
	s_nop 0
	flat_load_dwordx4 v[148:151], v[156:157] offset:256
	v_pk_mul_f32 v[90:91], v[90:91], v[136:137]
	v_lshlrev_b32_e32 v136, 16, v132
	v_lshlrev_b32_e32 v138, 16, v152
	v_and_b32_e32 v139, 0xffff0000, v152
	v_max_f32_e32 v138, v138, v138
	v_max_f32_e32 v139, v139, v139
	v_max_f32_e32 v138, 0xda24260, v138
	v_max_f32_e32 v139, 0xda24260, v139
	v_rcp_f32_e32 v138, v138
	v_rcp_f32_e32 v139, v139
	v_and_b32_e32 v137, 0xffff0000, v132
	v_lshlrev_b32_e32 v132, 16, v153
	v_max_f32_e32 v132, v132, v132
	v_max_f32_e32 v132, 0xda24260, v132
	v_pk_mul_f32 v[136:137], v[138:139], v[136:137]
	v_rcp_f32_e32 v138, v132
	v_and_b32_e32 v132, 0xffff0000, v153
	v_max_f32_e32 v132, v132, v132
	v_max_f32_e32 v132, 0xda24260, v132
	v_rcp_f32_e32 v139, v132
	v_pk_mul_f32 v[84:85], v[84:85], v[136:137]
	v_lshlrev_b32_e32 v136, 16, v154
	v_and_b32_e32 v137, 0xffff0000, v154
	v_max_f32_e32 v136, v136, v136
	v_max_f32_e32 v137, v137, v137
	v_lshlrev_b32_e32 v132, 16, v133
	v_and_b32_e32 v133, 0xffff0000, v133
	v_max_f32_e32 v136, 0xda24260, v136
	v_max_f32_e32 v137, 0xda24260, v137
	v_pk_mul_f32 v[132:133], v[138:139], v[132:133]
	v_rcp_f32_e32 v136, v136
	v_rcp_f32_e32 v137, v137
	v_pk_mul_f32 v[86:87], v[86:87], v[132:133]
	v_lshlrev_b32_e32 v132, 16, v134
	v_and_b32_e32 v133, 0xffff0000, v134
	v_lshlrev_b32_e32 v134, 16, v155
	v_max_f32_e32 v134, v134, v134
	v_max_f32_e32 v134, 0xda24260, v134
	v_pk_mul_f32 v[132:133], v[136:137], v[132:133]
	v_rcp_f32_e32 v136, v134
	v_and_b32_e32 v134, 0xffff0000, v155
	v_max_f32_e32 v134, v134, v134
	v_max_f32_e32 v134, 0xda24260, v134
	v_rcp_f32_e32 v137, v134
	v_pk_mul_f32 v[80:81], v[80:81], v[132:133]
	v_lshlrev_b32_e32 v132, 16, v135
	v_and_b32_e32 v133, 0xffff0000, v135
	v_add_co_u32_e32 v154, vcc, s65, v184
	s_waitcnt vmcnt(0) lgkmcnt(0)
; #define RT_(aw, pw, lo) ((lo ? bf_lo(aw) : bf_hi(aw)) * __builtin_amdgcn_rcpf(fmaxf(lo ? bf_lo(pw) : bf_hi(pw), 1e-30f)))
;     __device__ __forceinline__ void mid(f32x4 (&acc)[2][2][4][2], const Unit& u, int wr, int wc, int fr, int fq) const {
;         const int col0 = u.pn * BM + wc * 32 + 8 * fq, row0 = u.pm * BM + wr * 64 + fr;
;         unsigned long long ro_ = ((unsigned long long)row0 * 2048 + col0) * 2; asm volatile("" : "+v"(ro_));
;         const bf16_t* ga = (const bf16_t*)((const char*)GA + ro_); const bf16_t* gp = (const bf16_t*)((const char*)GP + ro_);
; #pragma unroll
;         for (int ai = 0; ai < 2; ++ai)
; #pragma unroll
;             for (int m = 0; m < 4; ++m)
; #pragma unroll
;                 for (int bj = 0; bj < 2; ++bj) { const size_t o_ = (size_t)(ai * HALF + m * 16) * 2048 + bj * HALF;
;                     const u32x4 a = *(const u32x4*)(ga + o_), p = *(const u32x4*)(gp + o_);
;     ...
;                     acc[ai][bj][m][0][0] *= RT_(a.x, p.x, 1); acc[ai][bj][m][0][1] *= RT_(a.x, p.x, 0); acc[ai][bj][m][0][2] *= RT_(a.y, p.y, 1); acc[ai][bj][m][0][3] *= RT_(a.y, p.y, 0);
;                     acc[ai][bj][m][1][0] *= RT_(a.z, p.z, 1); acc[ai][bj][m][1][1] *= RT_(a.z, p.z, 0); acc[ai][bj][m][1][2] *= RT_(a.w, p.w, 1); acc[ai][bj][m][1][3] *= RT_(a.w, p.w, 0);
;     ...
;                     asm volatile("" ::: "memory"); }
;     }
	v_lshlrev_b32_e32 v134, 16, v144
	v_and_b32_e32 v135, 0xffff0000, v144
	v_max_f32_e32 v134, v134, v134
	v_max_f32_e32 v135, v135, v135
	v_max_f32_e32 v134, 0xda24260, v134
	v_max_f32_e32 v135, 0xda24260, v135
	v_rcp_f32_e32 v134, v134
	v_rcp_f32_e32 v135, v135
	v_pk_mul_f32 v[132:133], v[136:137], v[132:133]
	v_addc_co_u32_e32 v155, vcc, 0, v185, vcc
	v_pk_mul_f32 v[82:83], v[82:83], v[132:133]
	v_lshlrev_b32_e32 v132, 16, v128
	v_and_b32_e32 v133, 0xffff0000, v128
	v_add_co_u32_e32 v156, vcc, s65, v182
	v_pk_mul_f32 v[152:153], v[134:135], v[132:133]
	s_nop 0
	v_addc_co_u32_e32 v157, vcc, 0, v183, vcc
	flat_load_dwordx4 v[132:135], v[154:155]
	flat_load_dwordx4 v[136:139], v[156:157]
	v_lshlrev_b32_e32 v128, 16, v145
	v_max_f32_e32 v128, v128, v128
	v_max_f32_e32 v128, 0xda24260, v128
	v_rcp_f32_e32 v144, v128
	v_and_b32_e32 v128, 0xffff0000, v145
	v_max_f32_e32 v128, v128, v128
	v_max_f32_e32 v128, 0xda24260, v128
	v_rcp_f32_e32 v145, v128
	v_lshlrev_b32_e32 v128, 16, v129
	v_and_b32_e32 v129, 0xffff0000, v129
	v_pk_mul_f32 v[128:129], v[144:145], v[128:129]
	v_lshlrev_b32_e32 v144, 16, v146
	v_and_b32_e32 v145, 0xffff0000, v146
	v_max_f32_e32 v144, v144, v144
	v_max_f32_e32 v145, v145, v145
	v_max_f32_e32 v144, 0xda24260, v144
	v_max_f32_e32 v145, 0xda24260, v145
	v_rcp_f32_e32 v144, v144
	v_rcp_f32_e32 v145, v145
	v_pk_mul_f32 v[78:79], v[78:79], v[128:129]
	v_lshlrev_b32_e32 v128, 16, v130
	v_and_b32_e32 v129, 0xffff0000, v130
	v_lshlrev_b32_e32 v130, 16, v147
	v_max_f32_e32 v130, v130, v130
	v_max_f32_e32 v130, 0xda24260, v130
	v_pk_mul_f32 v[128:129], v[144:145], v[128:129]
	v_rcp_f32_e32 v144, v130
	v_and_b32_e32 v130, 0xffff0000, v147
	v_max_f32_e32 v130, v130, v130
	v_max_f32_e32 v130, 0xda24260, v130
	v_rcp_f32_e32 v145, v130
	v_pk_mul_f32 v[72:73], v[72:73], v[128:129]
	v_lshlrev_b32_e32 v128, 16, v131
	v_and_b32_e32 v129, 0xffff0000, v131
	v_lshlrev_b32_e32 v130, 16, v148
	v_and_b32_e32 v131, 0xffff0000, v148
	v_max_f32_e32 v130, v130, v130
	v_max_f32_e32 v131, v131, v131
	v_max_f32_e32 v130, 0xda24260, v130
	v_max_f32_e32 v131, 0xda24260, v131
	v_rcp_f32_e32 v130, v130
	v_rcp_f32_e32 v131, v131
	v_pk_mul_f32 v[128:129], v[144:145], v[128:129]
	v_pk_mul_f32 v[76:77], v[76:77], v[152:153]
	v_pk_mul_f32 v[74:75], v[74:75], v[128:129]
	v_lshlrev_b32_e32 v128, 16, v140
	v_and_b32_e32 v129, 0xffff0000, v140
	v_pk_mul_f32 v[128:129], v[130:131], v[128:129]
	v_lshlrev_b32_e32 v130, 16, v149
	v_and_b32_e32 v131, 0xffff0000, v149
	v_max_f32_e32 v130, v130, v130
	v_max_f32_e32 v131, v131, v131
	v_max_f32_e32 v130, 0xda24260, v130
	v_max_f32_e32 v131, 0xda24260, v131
	v_rcp_f32_e32 v130, v130
	v_rcp_f32_e32 v131, v131
	flat_load_dwordx4 v[144:147], v[154:155] offset:256
	s_nop 0
	flat_load_dwordx4 v[152:155], v[156:157] offset:256
	v_pk_mul_f32 v[68:69], v[68:69], v[128:129]
	v_lshlrev_b32_e32 v128, 16, v141
	v_and_b32_e32 v129, 0xffff0000, v141
	v_pk_mul_f32 v[128:129], v[130:131], v[128:129]
	v_lshlrev_b32_e32 v130, 16, v150
	v_and_b32_e32 v131, 0xffff0000, v150
	v_max_f32_e32 v130, v130, v130
	v_max_f32_e32 v131, v131, v131
	v_max_f32_e32 v130, 0xda24260, v130
	v_max_f32_e32 v131, 0xda24260, v131
	v_rcp_f32_e32 v130, v130
	v_rcp_f32_e32 v131, v131
	v_pk_mul_f32 v[70:71], v[70:71], v[128:129]
	v_lshlrev_b32_e32 v128, 16, v142
	v_and_b32_e32 v129, 0xffff0000, v142
	v_pk_mul_f32 v[128:129], v[130:131], v[128:129]
	v_lshlrev_b32_e32 v130, 16, v151
	v_and_b32_e32 v131, 0xffff0000, v151
	v_max_f32_e32 v130, v130, v130
	v_max_f32_e32 v131, v131, v131
	v_max_f32_e32 v130, 0xda24260, v130
	v_max_f32_e32 v131, 0xda24260, v131
	v_rcp_f32_e32 v130, v130
	v_rcp_f32_e32 v131, v131
	v_pk_mul_f32 v[64:65], v[64:65], v[128:129]
	v_lshlrev_b32_e32 v128, 16, v143
	v_and_b32_e32 v129, 0xffff0000, v143
	v_pk_mul_f32 v[128:129], v[130:131], v[128:129]
	s_waitcnt vmcnt(0) lgkmcnt(0)
	v_lshlrev_b32_e32 v130, 16, v136
	v_and_b32_e32 v131, 0xffff0000, v136
	v_max_f32_e32 v130, v130, v130
	v_max_f32_e32 v131, v131, v131
	v_max_f32_e32 v130, 0xda24260, v130
	v_max_f32_e32 v131, 0xda24260, v131
	v_rcp_f32_e32 v130, v130
	v_rcp_f32_e32 v131, v131
	v_pk_mul_f32 v[66:67], v[66:67], v[128:129]
	v_lshlrev_b32_e32 v128, 16, v132
	v_and_b32_e32 v129, 0xffff0000, v132
	v_pk_mul_f32 v[148:149], v[130:131], v[128:129]
	v_lshlrev_b32_e32 v128, 16, v137
	v_max_f32_e32 v128, v128, v128
	v_max_f32_e32 v128, 0xda24260, v128
	v_rcp_f32_e32 v136, v128
	v_and_b32_e32 v128, 0xffff0000, v137
	v_add_co_u32_e32 v150, vcc, s66, v184
	v_max_f32_e32 v128, v128, v128
	s_nop 0
	v_addc_co_u32_e32 v151, vcc, 0, v185, vcc
	v_max_f32_e32 v128, 0xda24260, v128
	v_add_co_u32_e32 v156, vcc, s66, v182
	v_rcp_f32_e32 v137, v128
	s_nop 0
	v_addc_co_u32_e32 v157, vcc, 0, v183, vcc
	flat_load_dwordx4 v[128:131], v[150:151]
	flat_load_dwordx4 v[140:143], v[156:157]
	v_pk_mul_f32 v[60:61], v[60:61], v[148:149]
	flat_load_dwordx4 v[148:151], v[150:151] offset:256
	s_nop 0
	flat_load_dwordx4 v[156:159], v[156:157] offset:256
	v_lshlrev_b32_e32 v132, 16, v133
	v_and_b32_e32 v133, 0xffff0000, v133
	v_pk_mul_f32 v[132:133], v[136:137], v[132:133]
	v_lshlrev_b32_e32 v136, 16, v138
	v_and_b32_e32 v137, 0xffff0000, v138
	v_max_f32_e32 v136, v136, v136
	v_max_f32_e32 v137, v137, v137
	v_max_f32_e32 v136, 0xda24260, v136
	v_max_f32_e32 v137, 0xda24260, v137
	v_rcp_f32_e32 v136, v136
	v_rcp_f32_e32 v137, v137
	v_pk_mul_f32 v[62:63], v[62:63], v[132:133]
	v_lshlrev_b32_e32 v132, 16, v134
	v_and_b32_e32 v133, 0xffff0000, v134
	v_lshlrev_b32_e32 v134, 16, v139
	v_max_f32_e32 v134, v134, v134
	v_max_f32_e32 v134, 0xda24260, v134
	v_pk_mul_f32 v[132:133], v[136:137], v[132:133]
	v_rcp_f32_e32 v136, v134
; #define RT_(aw, pw, lo) ((lo ? bf_lo(aw) : bf_hi(aw)) * __builtin_amdgcn_rcpf(fmaxf(lo ? bf_lo(pw) : bf_hi(pw), 1e-30f)))
;     __device__ __forceinline__ void mid(f32x4 (&acc)[2][2][4][2], const Unit& u, int wr, int wc, int fr, int fq) const {
;         const int col0 = u.pn * BM + wc * 32 + 8 * fq, row0 = u.pm * BM + wr * 64 + fr;
;         unsigned long long ro_ = ((unsigned long long)row0 * 2048 + col0) * 2; asm volatile("" : "+v"(ro_));
;         const bf16_t* ga = (const bf16_t*)((const char*)GA + ro_); const bf16_t* gp = (const bf16_t*)((const char*)GP + ro_);
; #pragma unroll
;         for (int ai = 0; ai < 2; ++ai)
; #pragma unroll
;             for (int m = 0; m < 4; ++m)
; #pragma unroll
;                 for (int bj = 0; bj < 2; ++bj) { const size_t o_ = (size_t)(ai * HALF + m * 16) * 2048 + bj * HALF;
;                     const u32x4 a = *(const u32x4*)(ga + o_), p = *(const u32x4*)(gp + o_);
;     ...
;                     acc[ai][bj][m][0][0] *= RT_(a.x, p.x, 1); acc[ai][bj][m][0][1] *= RT_(a.x, p.x, 0); acc[ai][bj][m][0][2] *= RT_(a.y, p.y, 1); acc[ai][bj][m][0][3] *= RT_(a.y, p.y, 0);
;                     acc[ai][bj][m][1][0] *= RT_(a.z, p.z, 1); acc[ai][bj][m][1][1] *= RT_(a.z, p.z, 0); acc[ai][bj][m][1][2] *= RT_(a.w, p.w, 1); acc[ai][bj][m][1][3] *= RT_(a.w, p.w, 0);
;     ...
;                     asm volatile("" ::: "memory"); }
;     }
	v_and_b32_e32 v134, 0xffff0000, v139
	v_max_f32_e32 v134, v134, v134
	v_max_f32_e32 v134, 0xda24260, v134
	v_rcp_f32_e32 v137, v134
	v_pk_mul_f32 v[56:57], v[56:57], v[132:133]
	v_lshlrev_b32_e32 v132, 16, v135
	v_and_b32_e32 v133, 0xffff0000, v135
	v_lshlrev_b32_e32 v134, 16, v152
	v_and_b32_e32 v135, 0xffff0000, v152
	v_max_f32_e32 v134, v134, v134
	v_max_f32_e32 v135, v135, v135
	v_max_f32_e32 v134, 0xda24260, v134
	v_max_f32_e32 v135, 0xda24260, v135
	v_rcp_f32_e32 v134, v134
	v_rcp_f32_e32 v135, v135
	v_pk_mul_f32 v[132:133], v[136:137], v[132:133]
	s_nop 0
	v_pk_mul_f32 v[58:59], v[58:59], v[132:133]
	v_lshlrev_b32_e32 v132, 16, v144
	v_and_b32_e32 v133, 0xffff0000, v144
	v_pk_mul_f32 v[132:133], v[134:135], v[132:133]
	v_lshlrev_b32_e32 v134, 16, v153
	v_and_b32_e32 v135, 0xffff0000, v153
	v_max_f32_e32 v134, v134, v134
	v_max_f32_e32 v135, v135, v135
	v_max_f32_e32 v134, 0xda24260, v134
	v_max_f32_e32 v135, 0xda24260, v135
	v_rcp_f32_e32 v134, v134
	v_rcp_f32_e32 v135, v135
	v_pk_mul_f32 v[52:53], v[52:53], v[132:133]
	v_lshlrev_b32_e32 v132, 16, v145
	v_and_b32_e32 v133, 0xffff0000, v145
	v_pk_mul_f32 v[132:133], v[134:135], v[132:133]
	v_lshlrev_b32_e32 v134, 16, v154
	v_and_b32_e32 v135, 0xffff0000, v154
	v_max_f32_e32 v134, v134, v134
	v_max_f32_e32 v135, v135, v135
	v_max_f32_e32 v134, 0xda24260, v134
	v_max_f32_e32 v135, 0xda24260, v135
	v_rcp_f32_e32 v134, v134
	v_rcp_f32_e32 v135, v135
	v_pk_mul_f32 v[54:55], v[54:55], v[132:133]
	v_lshlrev_b32_e32 v132, 16, v146
	v_and_b32_e32 v133, 0xffff0000, v146
	v_pk_mul_f32 v[132:133], v[134:135], v[132:133]
	v_lshlrev_b32_e32 v134, 16, v155
	v_and_b32_e32 v135, 0xffff0000, v155
	v_max_f32_e32 v134, v134, v134
	v_max_f32_e32 v135, v135, v135
	v_max_f32_e32 v134, 0xda24260, v134
	v_max_f32_e32 v135, 0xda24260, v135
	v_rcp_f32_e32 v134, v134
	v_rcp_f32_e32 v135, v135
	v_pk_mul_f32 v[48:49], v[48:49], v[132:133]
	v_lshlrev_b32_e32 v132, 16, v147
	v_and_b32_e32 v133, 0xffff0000, v147
	v_pk_mul_f32 v[132:133], v[134:135], v[132:133]
	s_waitcnt vmcnt(0) lgkmcnt(0)
	v_lshlrev_b32_e32 v134, 16, v140
	v_pk_mul_f32 v[50:51], v[50:51], v[132:133]
	v_lshlrev_b32_e32 v132, 16, v128
	v_and_b32_e32 v133, 0xffff0000, v128
	v_lshlrev_b32_e32 v128, 16, v141
	v_max_f32_e32 v128, v128, v128
	v_and_b32_e32 v135, 0xffff0000, v140
	v_max_f32_e32 v128, 0xda24260, v128
	v_max_f32_e32 v134, v134, v134
	v_max_f32_e32 v135, v135, v135
	v_rcp_f32_e32 v140, v128
	v_and_b32_e32 v128, 0xffff0000, v141
	v_max_f32_e32 v134, 0xda24260, v134
	v_max_f32_e32 v135, 0xda24260, v135
	v_max_f32_e32 v128, v128, v128
	v_rcp_f32_e32 v134, v134
	v_rcp_f32_e32 v135, v135
	v_max_f32_e32 v128, 0xda24260, v128
	v_rcp_f32_e32 v141, v128
	v_add_co_u32_e32 v146, vcc, s67, v184
	v_pk_mul_f32 v[144:145], v[134:135], v[132:133]
	s_nop 0
	v_addc_co_u32_e32 v147, vcc, 0, v185, vcc
	v_add_co_u32_e32 v152, vcc, s67, v182
	v_lshlrev_b32_e32 v128, 16, v129
	s_nop 0
	v_addc_co_u32_e32 v153, vcc, 0, v183, vcc
	flat_load_dwordx4 v[132:135], v[146:147]
	flat_load_dwordx4 v[136:139], v[152:153]
	v_and_b32_e32 v129, 0xffff0000, v129
	v_pk_mul_f32 v[128:129], v[140:141], v[128:129]
	v_lshlrev_b32_e32 v140, 16, v142
	v_and_b32_e32 v141, 0xffff0000, v142
	v_max_f32_e32 v140, v140, v140
	v_max_f32_e32 v141, v141, v141
	v_max_f32_e32 v140, 0xda24260, v140
	v_max_f32_e32 v141, 0xda24260, v141
	v_rcp_f32_e32 v140, v140
	v_rcp_f32_e32 v141, v141
	v_pk_mul_f32 v[46:47], v[46:47], v[128:129]
	v_lshlrev_b32_e32 v128, 16, v130
	v_and_b32_e32 v129, 0xffff0000, v130
	v_lshlrev_b32_e32 v130, 16, v143
	v_max_f32_e32 v130, v130, v130
	v_max_f32_e32 v130, 0xda24260, v130
	v_pk_mul_f32 v[128:129], v[140:141], v[128:129]
	v_rcp_f32_e32 v140, v130
	v_and_b32_e32 v130, 0xffff0000, v143
	v_max_f32_e32 v130, v130, v130
	v_max_f32_e32 v130, 0xda24260, v130
	v_rcp_f32_e32 v141, v130
	v_pk_mul_f32 v[40:41], v[40:41], v[128:129]
	v_lshlrev_b32_e32 v128, 16, v131
	v_and_b32_e32 v129, 0xffff0000, v131
	v_lshlrev_b32_e32 v130, 16, v156
	v_and_b32_e32 v131, 0xffff0000, v156
	v_max_f32_e32 v130, v130, v130
	v_max_f32_e32 v131, v131, v131
	v_max_f32_e32 v130, 0xda24260, v130
	v_max_f32_e32 v131, 0xda24260, v131
	v_rcp_f32_e32 v130, v130
	v_rcp_f32_e32 v131, v131
	v_pk_mul_f32 v[128:129], v[140:141], v[128:129]
	v_pk_mul_f32 v[44:45], v[44:45], v[144:145]
	v_pk_mul_f32 v[42:43], v[42:43], v[128:129]
	v_lshlrev_b32_e32 v128, 16, v148
	v_and_b32_e32 v129, 0xffff0000, v148
	v_pk_mul_f32 v[128:129], v[130:131], v[128:129]
	v_lshlrev_b32_e32 v130, 16, v157
	v_and_b32_e32 v131, 0xffff0000, v157
	v_max_f32_e32 v130, v130, v130
	v_max_f32_e32 v131, v131, v131
	v_max_f32_e32 v130, 0xda24260, v130
	v_max_f32_e32 v131, 0xda24260, v131
	v_rcp_f32_e32 v130, v130
	v_rcp_f32_e32 v131, v131
	v_pk_mul_f32 v[36:37], v[36:37], v[128:129]
	v_lshlrev_b32_e32 v128, 16, v149
	v_and_b32_e32 v129, 0xffff0000, v149
	v_pk_mul_f32 v[144:145], v[130:131], v[128:129]
	v_lshlrev_b32_e32 v128, 16, v158
	v_max_f32_e32 v128, v128, v128
	v_max_f32_e32 v128, 0xda24260, v128
	v_rcp_f32_e32 v148, v128
	flat_load_dwordx4 v[128:131], v[146:147] offset:256
	flat_load_dwordx4 v[140:143], v[152:153] offset:256
	v_and_b32_e32 v146, 0xffff0000, v158
	v_max_f32_e32 v146, v146, v146
	v_max_f32_e32 v146, 0xda24260, v146
	v_rcp_f32_e32 v149, v146
	v_lshlrev_b32_e32 v146, 16, v159
	v_and_b32_e32 v147, 0xffff0000, v159
	v_max_f32_e32 v146, v146, v146
	v_max_f32_e32 v147, v147, v147
	v_max_f32_e32 v146, 0xda24260, v146
	v_max_f32_e32 v147, 0xda24260, v147
	v_rcp_f32_e32 v146, v146
	v_rcp_f32_e32 v147, v147
	v_pk_mul_f32 v[38:39], v[38:39], v[144:145]
	v_lshlrev_b32_e32 v144, 16, v150
	v_and_b32_e32 v145, 0xffff0000, v150
	v_pk_mul_f32 v[144:145], v[148:149], v[144:145]
	v_add_co_u32_e32 v154, vcc, s68, v184
	v_pk_mul_f32 v[32:33], v[32:33], v[144:145]
	v_lshlrev_b32_e32 v144, 16, v151
	v_and_b32_e32 v145, 0xffff0000, v151
	v_pk_mul_f32 v[144:145], v[146:147], v[144:145]
	s_waitcnt vmcnt(0) lgkmcnt(0)
; #define RT_(aw, pw, lo) ((lo ? bf_lo(aw) : bf_hi(aw)) * __builtin_amdgcn_rcpf(fmaxf(lo ? bf_lo(pw) : bf_hi(pw), 1e-30f)))
;     __device__ __forceinline__ void mid(f32x4 (&acc)[2][2][4][2], const Unit& u, int wr, int wc, int fr, int fq) const {
;         const int col0 = u.pn * BM + wc * 32 + 8 * fq, row0 = u.pm * BM + wr * 64 + fr;
;         unsigned long long ro_ = ((unsigned long long)row0 * 2048 + col0) * 2; asm volatile("" : "+v"(ro_));
;         const bf16_t* ga = (const bf16_t*)((const char*)GA + ro_); const bf16_t* gp = (const bf16_t*)((const char*)GP + ro_);
; #pragma unroll
;         for (int ai = 0; ai < 2; ++ai)
; #pragma unroll
;             for (int m = 0; m < 4; ++m)
; #pragma unroll
;                 for (int bj = 0; bj < 2; ++bj) { const size_t o_ = (size_t)(ai * HALF + m * 16) * 2048 + bj * HALF;
;                     const u32x4 a = *(const u32x4*)(ga + o_), p = *(const u32x4*)(gp + o_);
;     ...
;                     acc[ai][bj][m][0][0] *= RT_(a.x, p.x, 1); acc[ai][bj][m][0][1] *= RT_(a.x, p.x, 0); acc[ai][bj][m][0][2] *= RT_(a.y, p.y, 1); acc[ai][bj][m][0][3] *= RT_(a.y, p.y, 0);
;                     acc[ai][bj][m][1][0] *= RT_(a.z, p.z, 1); acc[ai][bj][m][1][1] *= RT_(a.z, p.z, 0); acc[ai][bj][m][1][2] *= RT_(a.w, p.w, 1); acc[ai][bj][m][1][3] *= RT_(a.w, p.w, 0);
;     ...
;                     asm volatile("" ::: "memory"); }
;     }
	v_lshlrev_b32_e32 v146, 16, v136
	v_and_b32_e32 v136, 0xffff0000, v136
	v_max_f32_e32 v146, v146, v146
	v_max_f32_e32 v136, v136, v136
	v_max_f32_e32 v146, 0xda24260, v146
	v_max_f32_e32 v136, 0xda24260, v136
	v_rcp_f32_e32 v146, v146
	v_rcp_f32_e32 v147, v136
	v_addc_co_u32_e32 v155, vcc, 0, v185, vcc
	v_pk_mul_f32 v[34:35], v[34:35], v[144:145]
	v_lshlrev_b32_e32 v144, 16, v132
	v_and_b32_e32 v145, 0xffff0000, v132
	v_add_co_u32_e32 v156, vcc, s68, v182
	v_pk_mul_f32 v[152:153], v[146:147], v[144:145]
	s_nop 0
	v_addc_co_u32_e32 v157, vcc, 0, v183, vcc
	flat_load_dwordx4 v[144:147], v[154:155]
	flat_load_dwordx4 v[148:151], v[156:157]
	v_lshlrev_b32_e32 v132, 16, v137
	v_max_f32_e32 v132, v132, v132
	v_max_f32_e32 v132, 0xda24260, v132
	v_rcp_f32_e32 v136, v132
	v_and_b32_e32 v132, 0xffff0000, v137
	v_max_f32_e32 v132, v132, v132
	v_max_f32_e32 v132, 0xda24260, v132
	v_rcp_f32_e32 v137, v132
	v_lshlrev_b32_e32 v132, 16, v133
	v_and_b32_e32 v133, 0xffff0000, v133
	v_pk_mul_f32 v[132:133], v[136:137], v[132:133]
	v_lshlrev_b32_e32 v136, 16, v138
	v_and_b32_e32 v137, 0xffff0000, v138
	v_max_f32_e32 v136, v136, v136
	v_max_f32_e32 v137, v137, v137
	v_max_f32_e32 v136, 0xda24260, v136
	v_max_f32_e32 v137, 0xda24260, v137
	v_rcp_f32_e32 v136, v136
	v_rcp_f32_e32 v137, v137
	v_pk_mul_f32 v[30:31], v[30:31], v[132:133]
	v_lshlrev_b32_e32 v132, 16, v134
	v_and_b32_e32 v133, 0xffff0000, v134
	v_lshlrev_b32_e32 v134, 16, v139
	v_max_f32_e32 v134, v134, v134
	v_max_f32_e32 v134, 0xda24260, v134
	v_pk_mul_f32 v[132:133], v[136:137], v[132:133]
	v_rcp_f32_e32 v136, v134
	v_and_b32_e32 v134, 0xffff0000, v139
	v_max_f32_e32 v134, v134, v134
	v_max_f32_e32 v134, 0xda24260, v134
	v_rcp_f32_e32 v137, v134
	v_pk_mul_f32 v[24:25], v[24:25], v[132:133]
	v_lshlrev_b32_e32 v132, 16, v135
	v_and_b32_e32 v133, 0xffff0000, v135
	v_pk_mul_f32 v[132:133], v[136:137], v[132:133]
	v_pk_mul_f32 v[28:29], v[28:29], v[152:153]
	v_lshlrev_b32_e32 v134, 16, v140
	v_and_b32_e32 v135, 0xffff0000, v140
	v_max_f32_e32 v134, v134, v134
	v_max_f32_e32 v135, v135, v135
	v_max_f32_e32 v134, 0xda24260, v134
	v_max_f32_e32 v135, 0xda24260, v135
	v_rcp_f32_e32 v134, v134
	v_rcp_f32_e32 v135, v135
	v_pk_mul_f32 v[26:27], v[26:27], v[132:133]
	v_lshlrev_b32_e32 v132, 16, v128
	v_and_b32_e32 v133, 0xffff0000, v128
	v_pk_mul_f32 v[152:153], v[134:135], v[132:133]
	flat_load_dwordx4 v[132:135], v[154:155] offset:256
	flat_load_dwordx4 v[136:139], v[156:157] offset:256
	v_lshlrev_b32_e32 v128, 16, v141
	v_max_f32_e32 v128, v128, v128
	v_max_f32_e32 v128, 0xda24260, v128
	v_rcp_f32_e32 v140, v128
	v_and_b32_e32 v128, 0xffff0000, v141
	v_max_f32_e32 v128, v128, v128
	v_max_f32_e32 v128, 0xda24260, v128
	v_rcp_f32_e32 v141, v128
	v_lshlrev_b32_e32 v128, 16, v129
	v_and_b32_e32 v129, 0xffff0000, v129
	v_pk_mul_f32 v[128:129], v[140:141], v[128:129]
	v_lshlrev_b32_e32 v140, 16, v142
	v_and_b32_e32 v141, 0xffff0000, v142
	v_max_f32_e32 v140, v140, v140
	v_max_f32_e32 v141, v141, v141
	v_max_f32_e32 v140, 0xda24260, v140
	v_max_f32_e32 v141, 0xda24260, v141
	v_rcp_f32_e32 v140, v140
	v_rcp_f32_e32 v141, v141
	v_pk_mul_f32 v[22:23], v[22:23], v[128:129]
	v_lshlrev_b32_e32 v128, 16, v130
	v_and_b32_e32 v129, 0xffff0000, v130
	v_lshlrev_b32_e32 v130, 16, v143
	v_max_f32_e32 v130, v130, v130
	v_max_f32_e32 v130, 0xda24260, v130
	v_pk_mul_f32 v[128:129], v[140:141], v[128:129]
	v_rcp_f32_e32 v140, v130
	v_and_b32_e32 v130, 0xffff0000, v143
	v_max_f32_e32 v130, v130, v130
	v_max_f32_e32 v130, 0xda24260, v130
	v_rcp_f32_e32 v141, v130
	v_pk_mul_f32 v[16:17], v[16:17], v[128:129]
	v_lshlrev_b32_e32 v128, 16, v131
	v_and_b32_e32 v129, 0xffff0000, v131
	s_waitcnt vmcnt(0) lgkmcnt(0)
; #define RT_(aw, pw, lo) ((lo ? bf_lo(aw) : bf_hi(aw)) * __builtin_amdgcn_rcpf(fmaxf(lo ? bf_lo(pw) : bf_hi(pw), 1e-30f)))
;     __device__ __forceinline__ void mid(f32x4 (&acc)[2][2][4][2], const Unit& u, int wr, int wc, int fr, int fq) const {
;         const int col0 = u.pn * BM + wc * 32 + 8 * fq, row0 = u.pm * BM + wr * 64 + fr;
;         unsigned long long ro_ = ((unsigned long long)row0 * 2048 + col0) * 2; asm volatile("" : "+v"(ro_));
;         const bf16_t* ga = (const bf16_t*)((const char*)GA + ro_); const bf16_t* gp = (const bf16_t*)((const char*)GP + ro_);
; #pragma unroll
;         for (int ai = 0; ai < 2; ++ai)
; #pragma unroll
;             for (int m = 0; m < 4; ++m)
; #pragma unroll
;                 for (int bj = 0; bj < 2; ++bj) { const size_t o_ = (size_t)(ai * HALF + m * 16) * 2048 + bj * HALF;
;                     const u32x4 a = *(const u32x4*)(ga + o_), p = *(const u32x4*)(gp + o_);
;     ...
;                     acc[ai][bj][m][0][0] *= RT_(a.x, p.x, 1); acc[ai][bj][m][0][1] *= RT_(a.x, p.x, 0); acc[ai][bj][m][0][2] *= RT_(a.y, p.y, 1); acc[ai][bj][m][0][3] *= RT_(a.y, p.y, 0);
;                     acc[ai][bj][m][1][0] *= RT_(a.z, p.z, 1); acc[ai][bj][m][1][1] *= RT_(a.z, p.z, 0); acc[ai][bj][m][1][2] *= RT_(a.w, p.w, 1); acc[ai][bj][m][1][3] *= RT_(a.w, p.w, 0);
;     ...
;                     asm volatile("" ::: "memory"); }
;     }
	v_lshlrev_b32_e32 v130, 16, v148
	v_and_b32_e32 v131, 0xffff0000, v148
	v_max_f32_e32 v130, v130, v130
	v_max_f32_e32 v131, v131, v131
	v_max_f32_e32 v130, 0xda24260, v130
	v_max_f32_e32 v131, 0xda24260, v131
	v_rcp_f32_e32 v130, v130
	v_rcp_f32_e32 v131, v131
	v_pk_mul_f32 v[128:129], v[140:141], v[128:129]
	s_waitcnt vmcnt(0)
	v_pk_mul_f32 v[20:21], v[20:21], v[152:153]
	v_pk_mul_f32 v[18:19], v[18:19], v[128:129]
	v_lshlrev_b32_e32 v128, 16, v144
	v_and_b32_e32 v129, 0xffff0000, v144
	v_pk_mul_f32 v[128:129], v[130:131], v[128:129]
	v_lshlrev_b32_e32 v130, 16, v149
	v_and_b32_e32 v131, 0xffff0000, v149
	v_max_f32_e32 v130, v130, v130
	v_max_f32_e32 v131, v131, v131
	v_max_f32_e32 v130, 0xda24260, v130
	v_max_f32_e32 v131, 0xda24260, v131
	v_rcp_f32_e32 v130, v130
	v_rcp_f32_e32 v131, v131
	v_pk_mul_f32 v[12:13], v[12:13], v[128:129]
	v_lshlrev_b32_e32 v128, 16, v145
	v_and_b32_e32 v129, 0xffff0000, v145
	v_pk_mul_f32 v[128:129], v[130:131], v[128:129]
	v_lshlrev_b32_e32 v130, 16, v150
	v_and_b32_e32 v131, 0xffff0000, v150
	v_max_f32_e32 v130, v130, v130
	v_max_f32_e32 v131, v131, v131
	v_max_f32_e32 v130, 0xda24260, v130
	v_max_f32_e32 v131, 0xda24260, v131
	v_rcp_f32_e32 v130, v130
	v_rcp_f32_e32 v131, v131
	v_pk_mul_f32 v[14:15], v[14:15], v[128:129]
	v_lshlrev_b32_e32 v128, 16, v146
	v_and_b32_e32 v129, 0xffff0000, v146
	v_pk_mul_f32 v[128:129], v[130:131], v[128:129]
	v_lshlrev_b32_e32 v130, 16, v151
	v_and_b32_e32 v131, 0xffff0000, v151
	v_max_f32_e32 v130, v130, v130
	v_max_f32_e32 v131, v131, v131
	v_max_f32_e32 v130, 0xda24260, v130
	v_max_f32_e32 v131, 0xda24260, v131
	v_rcp_f32_e32 v130, v130
	v_rcp_f32_e32 v131, v131
	v_pk_mul_f32 v[8:9], v[8:9], v[128:129]
	v_lshlrev_b32_e32 v128, 16, v147
	v_and_b32_e32 v129, 0xffff0000, v147
	v_pk_mul_f32 v[128:129], v[130:131], v[128:129]
	v_lshlrev_b32_e32 v130, 16, v136
	v_and_b32_e32 v131, 0xffff0000, v136
	v_max_f32_e32 v130, v130, v130
	v_max_f32_e32 v131, v131, v131
	v_max_f32_e32 v130, 0xda24260, v130
	v_max_f32_e32 v131, 0xda24260, v131
	v_rcp_f32_e32 v130, v130
	v_rcp_f32_e32 v131, v131
	v_pk_mul_f32 v[10:11], v[10:11], v[128:129]
	v_lshlrev_b32_e32 v128, 16, v132
	v_and_b32_e32 v129, 0xffff0000, v132
	v_pk_mul_f32 v[128:129], v[130:131], v[128:129]
	v_lshlrev_b32_e32 v130, 16, v137
	v_and_b32_e32 v131, 0xffff0000, v137
	v_max_f32_e32 v130, v130, v130
	v_max_f32_e32 v131, v131, v131
	v_max_f32_e32 v130, 0xda24260, v130
	v_max_f32_e32 v131, 0xda24260, v131
	v_rcp_f32_e32 v130, v130
	v_rcp_f32_e32 v131, v131
	v_pk_mul_f32 v[4:5], v[4:5], v[128:129]
	v_lshlrev_b32_e32 v128, 16, v133
	v_and_b32_e32 v129, 0xffff0000, v133
	v_pk_mul_f32 v[128:129], v[130:131], v[128:129]
	v_lshlrev_b32_e32 v130, 16, v138
	v_and_b32_e32 v131, 0xffff0000, v138
	v_max_f32_e32 v130, v130, v130
	v_max_f32_e32 v131, v131, v131
	v_max_f32_e32 v130, 0xda24260, v130
	v_max_f32_e32 v131, 0xda24260, v131
	v_rcp_f32_e32 v130, v130
	v_rcp_f32_e32 v131, v131
	v_pk_mul_f32 v[6:7], v[6:7], v[128:129]
	v_lshlrev_b32_e32 v128, 16, v134
	v_and_b32_e32 v129, 0xffff0000, v134
	v_pk_mul_f32 v[128:129], v[130:131], v[128:129]
	v_lshlrev_b32_e32 v130, 16, v139
	v_and_b32_e32 v131, 0xffff0000, v139
	v_max_f32_e32 v130, v130, v130
	v_max_f32_e32 v131, v131, v131
	v_max_f32_e32 v130, 0xda24260, v130
	v_max_f32_e32 v131, 0xda24260, v131
	v_rcp_f32_e32 v130, v130
	v_rcp_f32_e32 v131, v131
	v_pk_mul_f32 v[0:1], v[0:1], v[128:129]
	v_lshlrev_b32_e32 v128, 16, v135
	v_and_b32_e32 v129, 0xffff0000, v135
	v_pk_mul_f32 v[128:129], v[130:131], v[128:129]
	s_nop 0
	v_pk_mul_f32 v[2:3], v[2:3], v[128:129]
	.p2align	6

;     __host__ __device__ bool next(int i, Unit& u) const { return i < cnt ? so.next(base + i, u) : false; }
;     __host__ __device__ bool next(int i, Unit& u) const { const int L = i * G + c; if (L >= 32) return false; u.g = L >> 3; u.pm = L & 7; u.pn = 0; return true; }
;   __device__ __forceinline__ bool next(int i,AttnUnit&u)const{ if(i>=4)return false; const int s=vcu&7; u.bh=vcu>>3; u.qb=(i==0)?s:(i==1)?15-s:(i==2)?16+s:31-s; return true; }
; template <class Epi, class Sched, bool ALIGN_EPI = false, bool SP2 = false>
; __device__ __forceinline__ void gemm_phase(PG8_LAS unsigned char* lds, const Gemm g, const Sched& S, const Epi& E) {
;     ...
;         const bool has_next = S.next(ui + 1, nxt);
;         const char* nA = has_next ? (const char*)(g.A + (size_t)nxt.g * g.gsA) + (size_t)nxt.pm * tstepA : cA; const char* nB = has_next ? (const char*)(g.Bt + (size_t)nxt.g * g.gsB) + (size_t)nxt.pn * tstepB : cB;
;         for (int t = 0; t < nt; t += 2) {
;             if constexpr (Epi::MIDK) { if (t == (nt >> 1)) { asm volatile("s_waitcnt vmcnt(0)" ::: "memory"); E.mid(acc, cur, wr, wc, fr, fq); asm volatile("s_waitcnt vmcnt(0)" ::: "memory"); } }
;             const bool last = (t == nt - 2);
;             const char* a1 = cA + (size_t)(t + 1) * kstep;
;             const char* a2 = last ? nA : cA + (size_t)(t + 2) * kstep; const char* b2 = last ? nB : cB + (size_t)(t + 2) * kstep;
;             const char* a3 = a2 + kstep; const char* b3 = b2 + kstep;
;     ...
; #pragma unroll
;         for (int a = 0; a < 2; ++a)
; #pragma unroll
;             for (int b = 0; b < 2; ++b)
; #pragma unroll
;                 for (int m = 0; m < 4; ++m)
; #pragma unroll
;                     for (int n = 0; n < 2; ++n) acc[a][b][m][n] = (f32x4){0.f, 0.f, 0.f, 0.f};
.LBB0_742:
	s_ashr_i32 s31, s30, 31
	s_lshl_b64 s[34:35], s[30:31], 20
	s_add_u32 s34, s39, s34
	s_addc_u32 s35, s48, s35
	s_ashr_i32 s29, s28, 31
	s_lshl_b64 s[36:37], s[28:29], 20
	s_add_u32 s36, s49, s36
	v_mov_b32_e32 v123, 0
	s_addc_u32 s37, s50, s37
	s_andn2_b64 vcc, exec, s[16:17]
	v_mov_b32_e32 v122, v123
	v_mov_b32_e32 v121, v123
	v_mov_b32_e32 v120, v123
	v_mov_b32_e32 v127, v123
	v_mov_b32_e32 v126, v123
	v_mov_b32_e32 v125, v123
	v_mov_b32_e32 v124, v123
	v_mov_b32_e32 v111, v123
	v_mov_b32_e32 v110, v123
	v_mov_b32_e32 v109, v123
	v_mov_b32_e32 v108, v123
	v_mov_b32_e32 v107, v123
	v_mov_b32_e32 v106, v123
	v_mov_b32_e32 v105, v123
	v_mov_b32_e32 v104, v123
	v_mov_b32_e32 v95, v123
	v_mov_b32_e32 v94, v123
	v_mov_b32_e32 v93, v123
	v_mov_b32_e32 v92, v123
	v_mov_b32_e32 v91, v123
	v_mov_b32_e32 v90, v123
	v_mov_b32_e32 v89, v123
	v_mov_b32_e32 v88, v123
	v_mov_b32_e32 v79, v123
	v_mov_b32_e32 v78, v123
	v_mov_b32_e32 v77, v123
	v_mov_b32_e32 v76, v123
	v_mov_b32_e32 v75, v123
	v_mov_b32_e32 v74, v123
	v_mov_b32_e32 v73, v123
	v_mov_b32_e32 v72, v123
	v_mov_b32_e32 v119, v123
	v_mov_b32_e32 v118, v123
	v_mov_b32_e32 v117, v123
	v_mov_b32_e32 v116, v123
	v_mov_b32_e32 v115, v123
	v_mov_b32_e32 v114, v123
	v_mov_b32_e32 v113, v123
	v_mov_b32_e32 v112, v123
	v_mov_b32_e32 v103, v123
	v_mov_b32_e32 v102, v123
	v_mov_b32_e32 v101, v123
	v_mov_b32_e32 v100, v123
	v_mov_b32_e32 v99, v123
	v_mov_b32_e32 v98, v123
	v_mov_b32_e32 v97, v123
	v_mov_b32_e32 v96, v123
	v_mov_b32_e32 v87, v123
	v_mov_b32_e32 v86, v123
	v_mov_b32_e32 v85, v123
	v_mov_b32_e32 v84, v123
	v_mov_b32_e32 v83, v123
	v_mov_b32_e32 v82, v123
	v_mov_b32_e32 v81, v123
	v_mov_b32_e32 v80, v123
	v_mov_b32_e32 v71, v123
	v_mov_b32_e32 v70, v123
	v_mov_b32_e32 v69, v123
	v_mov_b32_e32 v68, v123
	v_mov_b32_e32 v67, v123
	v_mov_b32_e32 v66, v123
	v_mov_b32_e32 v65, v123
	v_mov_b32_e32 v64, v123
	v_mov_b32_e32 v63, v123
	v_mov_b32_e32 v62, v123
	v_mov_b32_e32 v61, v123
	v_mov_b32_e32 v60, v123
	v_mov_b32_e32 v59, v123
	v_mov_b32_e32 v58, v123
	v_mov_b32_e32 v57, v123
	v_mov_b32_e32 v56, v123
	v_mov_b32_e32 v47, v123
	v_mov_b32_e32 v46, v123
	v_mov_b32_e32 v45, v123
	v_mov_b32_e32 v44, v123
	v_mov_b32_e32 v43, v123
	v_mov_b32_e32 v42, v123
	v_mov_b32_e32 v41, v123
	v_mov_b32_e32 v40, v123
	v_mov_b32_e32 v31, v123
	v_mov_b32_e32 v30, v123
	v_mov_b32_e32 v29, v123
	v_mov_b32_e32 v28, v123
	v_mov_b32_e32 v27, v123
	v_mov_b32_e32 v26, v123
	v_mov_b32_e32 v25, v123
	v_mov_b32_e32 v24, v123
	v_mov_b32_e32 v15, v123
	v_mov_b32_e32 v14, v123
	v_mov_b32_e32 v13, v123
	v_mov_b32_e32 v12, v123
	v_mov_b32_e32 v11, v123
	v_mov_b32_e32 v10, v123
	v_mov_b32_e32 v9, v123
	v_mov_b32_e32 v8, v123
	v_mov_b32_e32 v55, v123
	v_mov_b32_e32 v54, v123
	v_mov_b32_e32 v53, v123
	v_mov_b32_e32 v52, v123
	v_mov_b32_e32 v51, v123
	v_mov_b32_e32 v50, v123
	v_mov_b32_e32 v49, v123
	v_mov_b32_e32 v48, v123
	v_mov_b32_e32 v39, v123
	v_mov_b32_e32 v38, v123
	v_mov_b32_e32 v37, v123
	v_mov_b32_e32 v36, v123
	v_mov_b32_e32 v35, v123
	v_mov_b32_e32 v34, v123
	v_mov_b32_e32 v33, v123
	v_mov_b32_e32 v32, v123
	v_mov_b32_e32 v23, v123
	v_mov_b32_e32 v22, v123
	v_mov_b32_e32 v21, v123
	v_mov_b32_e32 v20, v123
	v_mov_b32_e32 v19, v123
	v_mov_b32_e32 v18, v123
	v_mov_b32_e32 v17, v123
	v_mov_b32_e32 v16, v123
	v_mov_b32_e32 v7, v123
	v_mov_b32_e32 v6, v123
	v_mov_b32_e32 v5, v123
	v_mov_b32_e32 v4, v123
	s_waitcnt lgkmcnt(0)
	v_mov_b32_e32 v3, v123
	v_mov_b32_e32 v2, v123
	v_mov_b32_e32 v1, v123
	v_mov_b32_e32 v0, v123
	s_cbranch_vccnz .LBB0_745
	s_and_b64 s[46:47], s[6:7], exec
	s_cselect_b32 s29, s35, s45
	s_cselect_b32 s31, s34, s44
	s_cselect_b32 s63, s37, s43
	s_cselect_b32 s64, s36, s42
	s_add_u32 s65, s42, 0x100
	s_addc_u32 s66, s43, 0
	s_add_u32 s42, s44, 0x80080
	v_mov_b32_e32 v0, 0
	s_addc_u32 s43, s45, 0
	s_mov_b32 s44, 0
	v_mov_b32_e32 v1, v0
	v_mov_b32_e32 v2, v0
	v_mov_b32_e32 v3, v0
	v_mov_b32_e32 v4, v0
	v_mov_b32_e32 v5, v0
	v_mov_b32_e32 v6, v0
	v_mov_b32_e32 v7, v0
	v_mov_b32_e32 v16, v0
	v_mov_b32_e32 v17, v0
	v_mov_b32_e32 v18, v0
	v_mov_b32_e32 v19, v0
	v_mov_b32_e32 v20, v0
	v_mov_b32_e32 v21, v0
	v_mov_b32_e32 v22, v0
	v_mov_b32_e32 v23, v0
	v_mov_b32_e32 v32, v0
	v_mov_b32_e32 v33, v0
	v_mov_b32_e32 v34, v0
	v_mov_b32_e32 v35, v0
	v_mov_b32_e32 v36, v0
	v_mov_b32_e32 v37, v0
	v_mov_b32_e32 v38, v0
	v_mov_b32_e32 v39, v0
	v_mov_b32_e32 v48, v0
	v_mov_b32_e32 v49, v0
	v_mov_b32_e32 v50, v0
	v_mov_b32_e32 v51, v0
	v_mov_b32_e32 v52, v0
	v_mov_b32_e32 v53, v0
	v_mov_b32_e32 v54, v0
	v_mov_b32_e32 v55, v0
	v_mov_b32_e32 v8, v0
	v_mov_b32_e32 v9, v0
	v_mov_b32_e32 v10, v0
	v_mov_b32_e32 v11, v0
	v_mov_b32_e32 v12, v0
	v_mov_b32_e32 v13, v0
	v_mov_b32_e32 v14, v0
	v_mov_b32_e32 v15, v0
	v_mov_b32_e32 v24, v0
	v_mov_b32_e32 v25, v0
	v_mov_b32_e32 v26, v0
	v_mov_b32_e32 v27, v0
	v_mov_b32_e32 v28, v0
	v_mov_b32_e32 v29, v0
	v_mov_b32_e32 v30, v0
	v_mov_b32_e32 v31, v0
	v_mov_b32_e32 v40, v0
	v_mov_b32_e32 v41, v0
	v_mov_b32_e32 v42, v0
	v_mov_b32_e32 v43, v0
	v_mov_b32_e32 v44, v0
	v_mov_b32_e32 v45, v0
	v_mov_b32_e32 v46, v0
	v_mov_b32_e32 v47, v0
	v_mov_b32_e32 v56, v0
	v_mov_b32_e32 v57, v0
	v_mov_b32_e32 v58, v0
	v_mov_b32_e32 v59, v0
	v_mov_b32_e32 v60, v0
	v_mov_b32_e32 v61, v0
	v_mov_b32_e32 v62, v0
	v_mov_b32_e32 v63, v0
	v_mov_b32_e32 v64, v0
	v_mov_b32_e32 v65, v0
	v_mov_b32_e32 v66, v0
	v_mov_b32_e32 v67, v0
	v_mov_b32_e32 v68, v0
	v_mov_b32_e32 v69, v0
	v_mov_b32_e32 v70, v0
	v_mov_b32_e32 v71, v0
	v_mov_b32_e32 v80, v0
	v_mov_b32_e32 v81, v0
	v_mov_b32_e32 v82, v0
	v_mov_b32_e32 v83, v0
	v_mov_b32_e32 v84, v0
	v_mov_b32_e32 v85, v0
	v_mov_b32_e32 v86, v0
	v_mov_b32_e32 v87, v0
	v_mov_b32_e32 v96, v0
	v_mov_b32_e32 v97, v0
	v_mov_b32_e32 v98, v0
	v_mov_b32_e32 v99, v0
	v_mov_b32_e32 v100, v0
	v_mov_b32_e32 v101, v0
	v_mov_b32_e32 v102, v0
	v_mov_b32_e32 v103, v0
	v_mov_b32_e32 v112, v0
	v_mov_b32_e32 v113, v0
	v_mov_b32_e32 v114, v0
	v_mov_b32_e32 v115, v0
	v_mov_b32_e32 v116, v0
	v_mov_b32_e32 v117, v0
	v_mov_b32_e32 v118, v0
	v_mov_b32_e32 v119, v0
	v_mov_b32_e32 v72, v0
	v_mov_b32_e32 v73, v0
	v_mov_b32_e32 v74, v0
	v_mov_b32_e32 v75, v0
	v_mov_b32_e32 v76, v0
	v_mov_b32_e32 v77, v0
	v_mov_b32_e32 v78, v0
	v_mov_b32_e32 v79, v0
	v_mov_b32_e32 v88, v0
	v_mov_b32_e32 v89, v0
	v_mov_b32_e32 v90, v0
	v_mov_b32_e32 v91, v0
	v_mov_b32_e32 v92, v0
	v_mov_b32_e32 v93, v0
	v_mov_b32_e32 v94, v0
	v_mov_b32_e32 v95, v0
	v_mov_b32_e32 v104, v0
	v_mov_b32_e32 v105, v0
	v_mov_b32_e32 v106, v0
	v_mov_b32_e32 v107, v0
	v_mov_b32_e32 v108, v0
	v_mov_b32_e32 v109, v0
	v_mov_b32_e32 v110, v0
	v_mov_b32_e32 v111, v0
	v_mov_b32_e32 v124, v0
	v_mov_b32_e32 v125, v0
	v_mov_b32_e32 v126, v0
	v_mov_b32_e32 v127, v0
	v_mov_b32_e32 v120, v0
	v_mov_b32_e32 v121, v0
	v_mov_b32_e32 v122, v0
	v_mov_b32_e32 v123, v0
	.p2align	6

;     __host__ __device__ bool next(int i, Unit& u) const { return i < cnt ? so.next(base + i, u) : false; }
;     __host__ __device__ bool next(int i, Unit& u) const { const int L = i * G + c; if (L >= 32) return false; u.g = L >> 3; u.pm = L & 7; u.pn = 0; return true; }
;   __device__ __forceinline__ bool next(int i,AttnUnit&u)const{ if(i>=4)return false; const int s=vcu&7; u.bh=vcu>>3; u.qb=(i==0)?s:(i==1)?15-s:(i==2)?16+s:31-s; return true; }
; template <class Epi, class Sched, bool ALIGN_EPI = false, bool SP2 = false>
; __device__ __forceinline__ void gemm_phase(PG8_LAS unsigned char* lds, const Gemm g, const Sched& S, const Epi& E) {
;     ...
;         const bool has_next = S.next(ui + 1, nxt);
;         const char* nA = has_next ? (const char*)(g.A + (size_t)nxt.g * g.gsA) + (size_t)nxt.pm * tstepA : cA; const char* nB = has_next ? (const char*)(g.Bt + (size_t)nxt.g * g.gsB) + (size_t)nxt.pn * tstepB : cB;
;         for (int t = 0; t < nt; t += 2) {
;             if constexpr (Epi::MIDK) { if (t == (nt >> 1)) { asm volatile("s_waitcnt vmcnt(0)" ::: "memory"); E.mid(acc, cur, wr, wc, fr, fq); asm volatile("s_waitcnt vmcnt(0)" ::: "memory"); } }
;             const bool last = (t == nt - 2);
;             const char* a1 = cA + (size_t)(t + 1) * kstep;
;             const char* a2 = last ? nA : cA + (size_t)(t + 2) * kstep; const char* b2 = last ? nB : cB + (size_t)(t + 2) * kstep;
;             const char* a3 = a2 + kstep; const char* b3 = b2 + kstep;
;     ...
; #pragma unroll
;         for (int a = 0; a < 2; ++a)
; #pragma unroll
;             for (int b = 0; b < 2; ++b)
; #pragma unroll
;                 for (int m = 0; m < 4; ++m)
; #pragma unroll
;                     for (int n = 0; n < 2; ++n) acc[a][b][m][n] = (f32x4){0.f, 0.f, 0.f, 0.f};
.LBB0_827:
	s_ashr_i32 s35, s34, 31
	s_lshl_b64 s[36:37], s[34:35], 20
	s_add_u32 s36, s47, s36
	s_addc_u32 s37, s48, s37
	s_ashr_i32 s31, s30, 31
	s_lshl_b64 s[38:39], s[30:31], 20
	s_add_u32 s38, s49, s38
	v_mov_b32_e32 v123, 0
	s_addc_u32 s39, s50, s39
	s_andn2_b64 vcc, exec, s[18:19]
	v_mov_b32_e32 v122, v123
	v_mov_b32_e32 v121, v123
	v_mov_b32_e32 v120, v123
	v_mov_b32_e32 v127, v123
	v_mov_b32_e32 v126, v123
	v_mov_b32_e32 v125, v123
	v_mov_b32_e32 v124, v123
	v_mov_b32_e32 v111, v123
	v_mov_b32_e32 v110, v123
	v_mov_b32_e32 v109, v123
	v_mov_b32_e32 v108, v123
	v_mov_b32_e32 v107, v123
	v_mov_b32_e32 v106, v123
	v_mov_b32_e32 v105, v123
	v_mov_b32_e32 v104, v123
	v_mov_b32_e32 v95, v123
	v_mov_b32_e32 v94, v123
	v_mov_b32_e32 v93, v123
	v_mov_b32_e32 v92, v123
	v_mov_b32_e32 v91, v123
	v_mov_b32_e32 v90, v123
	v_mov_b32_e32 v89, v123
	v_mov_b32_e32 v88, v123
	v_mov_b32_e32 v79, v123
	v_mov_b32_e32 v78, v123
	v_mov_b32_e32 v77, v123
	v_mov_b32_e32 v76, v123
	v_mov_b32_e32 v75, v123
	v_mov_b32_e32 v74, v123
	v_mov_b32_e32 v73, v123
	v_mov_b32_e32 v72, v123
	v_mov_b32_e32 v119, v123
	v_mov_b32_e32 v118, v123
	v_mov_b32_e32 v117, v123
	v_mov_b32_e32 v116, v123
	v_mov_b32_e32 v115, v123
	v_mov_b32_e32 v114, v123
	v_mov_b32_e32 v113, v123
	v_mov_b32_e32 v112, v123
	v_mov_b32_e32 v103, v123
	v_mov_b32_e32 v102, v123
	v_mov_b32_e32 v101, v123
	v_mov_b32_e32 v100, v123
	v_mov_b32_e32 v99, v123
	v_mov_b32_e32 v98, v123
	v_mov_b32_e32 v97, v123
	v_mov_b32_e32 v96, v123
	v_mov_b32_e32 v87, v123
	v_mov_b32_e32 v86, v123
	v_mov_b32_e32 v85, v123
	v_mov_b32_e32 v84, v123
	v_mov_b32_e32 v83, v123
	v_mov_b32_e32 v82, v123
	v_mov_b32_e32 v81, v123
	v_mov_b32_e32 v80, v123
	v_mov_b32_e32 v71, v123
	v_mov_b32_e32 v70, v123
	v_mov_b32_e32 v69, v123
	v_mov_b32_e32 v68, v123
	v_mov_b32_e32 v67, v123
	v_mov_b32_e32 v66, v123
	v_mov_b32_e32 v65, v123
	v_mov_b32_e32 v64, v123
	v_mov_b32_e32 v63, v123
	v_mov_b32_e32 v62, v123
	v_mov_b32_e32 v61, v123
	v_mov_b32_e32 v60, v123
	v_mov_b32_e32 v59, v123
	v_mov_b32_e32 v58, v123
	v_mov_b32_e32 v57, v123
	v_mov_b32_e32 v56, v123
	v_mov_b32_e32 v47, v123
	v_mov_b32_e32 v46, v123
	v_mov_b32_e32 v45, v123
	v_mov_b32_e32 v44, v123
	v_mov_b32_e32 v43, v123
	v_mov_b32_e32 v42, v123
	v_mov_b32_e32 v41, v123
	v_mov_b32_e32 v40, v123
	v_mov_b32_e32 v31, v123
	v_mov_b32_e32 v30, v123
	v_mov_b32_e32 v29, v123
	v_mov_b32_e32 v28, v123
	v_mov_b32_e32 v27, v123
	v_mov_b32_e32 v26, v123
	v_mov_b32_e32 v25, v123
	v_mov_b32_e32 v24, v123
	v_mov_b32_e32 v15, v123
	v_mov_b32_e32 v14, v123
	v_mov_b32_e32 v13, v123
	v_mov_b32_e32 v12, v123
	v_mov_b32_e32 v11, v123
	v_mov_b32_e32 v10, v123
	v_mov_b32_e32 v9, v123
	v_mov_b32_e32 v8, v123
	v_mov_b32_e32 v55, v123
	v_mov_b32_e32 v54, v123
	v_mov_b32_e32 v53, v123
	v_mov_b32_e32 v52, v123
	v_mov_b32_e32 v51, v123
	v_mov_b32_e32 v50, v123
	v_mov_b32_e32 v49, v123
	v_mov_b32_e32 v48, v123
	v_mov_b32_e32 v39, v123
	v_mov_b32_e32 v38, v123
	v_mov_b32_e32 v37, v123
	v_mov_b32_e32 v36, v123
	v_mov_b32_e32 v35, v123
	v_mov_b32_e32 v34, v123
	v_mov_b32_e32 v33, v123
	v_mov_b32_e32 v32, v123
	v_mov_b32_e32 v23, v123
	v_mov_b32_e32 v22, v123
	v_mov_b32_e32 v21, v123
	v_mov_b32_e32 v20, v123
	v_mov_b32_e32 v19, v123
	v_mov_b32_e32 v18, v123
	v_mov_b32_e32 v17, v123
	v_mov_b32_e32 v16, v123
	v_mov_b32_e32 v7, v123
	v_mov_b32_e32 v6, v123
	v_mov_b32_e32 v5, v123
	v_mov_b32_e32 v4, v123
	v_mov_b32_e32 v3, v123
	v_mov_b32_e32 v2, v123
	v_mov_b32_e32 v1, v123
	v_mov_b32_e32 v0, v123
	s_cbranch_vccnz .LBB0_830
	s_and_b64 s[44:45], s[6:7], exec
	s_cselect_b32 s31, s37, s43
	s_cselect_b32 s35, s36, s42
	s_cselect_b32 s67, s39, s41
	s_cselect_b32 s68, s38, s40
	s_add_u32 s69, s40, 0x100
	s_addc_u32 s70, s41, 0
	s_add_u32 s40, s42, 0x80080
	v_mov_b32_e32 v0, 0
	s_addc_u32 s41, s43, 0
	s_mov_b32 s42, 0
	v_mov_b32_e32 v1, v0
	v_mov_b32_e32 v2, v0
	v_mov_b32_e32 v3, v0
	v_mov_b32_e32 v4, v0
	v_mov_b32_e32 v5, v0
	v_mov_b32_e32 v6, v0
	v_mov_b32_e32 v7, v0
	v_mov_b32_e32 v16, v0
	v_mov_b32_e32 v17, v0
	v_mov_b32_e32 v18, v0
	v_mov_b32_e32 v19, v0
	v_mov_b32_e32 v20, v0
	v_mov_b32_e32 v21, v0
	v_mov_b32_e32 v22, v0
	v_mov_b32_e32 v23, v0
	v_mov_b32_e32 v32, v0
	v_mov_b32_e32 v33, v0
	v_mov_b32_e32 v34, v0
	v_mov_b32_e32 v35, v0
	v_mov_b32_e32 v36, v0
	v_mov_b32_e32 v37, v0
	v_mov_b32_e32 v38, v0
	v_mov_b32_e32 v39, v0
	v_mov_b32_e32 v48, v0
	v_mov_b32_e32 v49, v0
	v_mov_b32_e32 v50, v0
	v_mov_b32_e32 v51, v0
	v_mov_b32_e32 v52, v0
	v_mov_b32_e32 v53, v0
	v_mov_b32_e32 v54, v0
	v_mov_b32_e32 v55, v0
	v_mov_b32_e32 v8, v0
	v_mov_b32_e32 v9, v0
	v_mov_b32_e32 v10, v0
	v_mov_b32_e32 v11, v0
	v_mov_b32_e32 v12, v0
	v_mov_b32_e32 v13, v0
	v_mov_b32_e32 v14, v0
	v_mov_b32_e32 v15, v0
	v_mov_b32_e32 v24, v0
	v_mov_b32_e32 v25, v0
	v_mov_b32_e32 v26, v0
	v_mov_b32_e32 v27, v0
	v_mov_b32_e32 v28, v0
	v_mov_b32_e32 v29, v0
	v_mov_b32_e32 v30, v0
	v_mov_b32_e32 v31, v0
	v_mov_b32_e32 v40, v0
	v_mov_b32_e32 v41, v0
	v_mov_b32_e32 v42, v0
	v_mov_b32_e32 v43, v0
	v_mov_b32_e32 v44, v0
	v_mov_b32_e32 v45, v0
	v_mov_b32_e32 v46, v0
	v_mov_b32_e32 v47, v0
	v_mov_b32_e32 v56, v0
	v_mov_b32_e32 v57, v0
	v_mov_b32_e32 v58, v0
	v_mov_b32_e32 v59, v0
	v_mov_b32_e32 v60, v0
	v_mov_b32_e32 v61, v0
	v_mov_b32_e32 v62, v0
	v_mov_b32_e32 v63, v0
	v_mov_b32_e32 v64, v0
	v_mov_b32_e32 v65, v0
	v_mov_b32_e32 v66, v0
	v_mov_b32_e32 v67, v0
	v_mov_b32_e32 v68, v0
	v_mov_b32_e32 v69, v0
	v_mov_b32_e32 v70, v0
	v_mov_b32_e32 v71, v0
	v_mov_b32_e32 v80, v0
	v_mov_b32_e32 v81, v0
	v_mov_b32_e32 v82, v0
	v_mov_b32_e32 v83, v0
	v_mov_b32_e32 v84, v0
	v_mov_b32_e32 v85, v0
	v_mov_b32_e32 v86, v0
	v_mov_b32_e32 v87, v0
	v_mov_b32_e32 v96, v0
	v_mov_b32_e32 v97, v0
	v_mov_b32_e32 v98, v0
	v_mov_b32_e32 v99, v0
	v_mov_b32_e32 v100, v0
	v_mov_b32_e32 v101, v0
	v_mov_b32_e32 v102, v0
	v_mov_b32_e32 v103, v0
	v_mov_b32_e32 v112, v0
	v_mov_b32_e32 v113, v0
	v_mov_b32_e32 v114, v0
	v_mov_b32_e32 v115, v0
	v_mov_b32_e32 v116, v0
	v_mov_b32_e32 v117, v0
	v_mov_b32_e32 v118, v0
	v_mov_b32_e32 v119, v0
	v_mov_b32_e32 v72, v0
	v_mov_b32_e32 v73, v0
	v_mov_b32_e32 v74, v0
	v_mov_b32_e32 v75, v0
	v_mov_b32_e32 v76, v0
	v_mov_b32_e32 v77, v0
	v_mov_b32_e32 v78, v0
	v_mov_b32_e32 v79, v0
	v_mov_b32_e32 v88, v0
	v_mov_b32_e32 v89, v0
	v_mov_b32_e32 v90, v0
	v_mov_b32_e32 v91, v0
	v_mov_b32_e32 v92, v0
	v_mov_b32_e32 v93, v0
	v_mov_b32_e32 v94, v0
	v_mov_b32_e32 v95, v0
	v_mov_b32_e32 v104, v0
	v_mov_b32_e32 v105, v0
	v_mov_b32_e32 v106, v0
	v_mov_b32_e32 v107, v0
	v_mov_b32_e32 v108, v0
	v_mov_b32_e32 v109, v0
	v_mov_b32_e32 v110, v0
	v_mov_b32_e32 v111, v0
	v_mov_b32_e32 v124, v0
	v_mov_b32_e32 v125, v0
	v_mov_b32_e32 v126, v0
	v_mov_b32_e32 v127, v0
	v_mov_b32_e32 v120, v0
	v_mov_b32_e32 v121, v0
	v_mov_b32_e32 v122, v0
	v_mov_b32_e32 v123, v0
	.p2align	6

;     __host__ __device__ bool next(int i, Unit& u) const { return i < cnt ? so.next(base + i, u) : false; }
;     __host__ __device__ bool next(int i, Unit& u) const { const int L = i * G + c; if (L >= 32) return false; u.g = L >> 3; u.pm = L & 7; u.pn = 0; return true; }
;   __device__ __forceinline__ bool next(int i,AttnUnit&u)const{ if(i>=4)return false; const int s=vcu&7; u.bh=vcu>>3; u.qb=(i==0)?s:(i==1)?15-s:(i==2)?16+s:31-s; return true; }
; template <class Epi, class Sched, bool ALIGN_EPI = false, bool SP2 = false>
; __device__ __forceinline__ void gemm_phase(PG8_LAS unsigned char* lds, const Gemm g, const Sched& S, const Epi& E) {
;     ...
;         const bool has_next = S.next(ui + 1, nxt);
;         const char* nA = has_next ? (const char*)(g.A + (size_t)nxt.g * g.gsA) + (size_t)nxt.pm * tstepA : cA; const char* nB = has_next ? (const char*)(g.Bt + (size_t)nxt.g * g.gsB) + (size_t)nxt.pn * tstepB : cB;
;         for (int t = 0; t < nt; t += 2) {
;             if constexpr (Epi::MIDK) { if (t == (nt >> 1)) { asm volatile("s_waitcnt vmcnt(0)" ::: "memory"); E.mid(acc, cur, wr, wc, fr, fq); asm volatile("s_waitcnt vmcnt(0)" ::: "memory"); } }
;             const bool last = (t == nt - 2);
;             const char* a1 = cA + (size_t)(t + 1) * kstep;
;             const char* a2 = last ? nA : cA + (size_t)(t + 2) * kstep; const char* b2 = last ? nB : cB + (size_t)(t + 2) * kstep;
;             const char* a3 = a2 + kstep; const char* b3 = b2 + kstep;
;     ...
; #pragma unroll
;         for (int a = 0; a < 2; ++a)
; #pragma unroll
;             for (int b = 0; b < 2; ++b)
; #pragma unroll
;                 for (int m = 0; m < 4; ++m)
; #pragma unroll
;                     for (int n = 0; n < 2; ++n) acc[a][b][m][n] = (f32x4){0.f, 0.f, 0.f, 0.f};
.LBB0_897:
	s_ashr_i32 s29, s28, 31
	s_lshl_b64 s[30:31], s[28:29], 22
	s_add_u32 s30, s45, s30
	s_addc_u32 s31, s46, s31
	s_ashr_i32 s27, s26, 31
	s_lshl_b64 s[34:35], s[26:27], 22
	s_add_u32 s34, s47, s34
	v_mov_b32_e32 v127, 0
	s_addc_u32 s35, s48, s35
	s_andn2_b64 vcc, exec, s[12:13]
	v_mov_b32_e32 v126, v127
	v_mov_b32_e32 v125, v127
	v_mov_b32_e32 v124, v127
	v_mov_b32_e32 v123, v127
	v_mov_b32_e32 v122, v127
	v_mov_b32_e32 v121, v127
	v_mov_b32_e32 v120, v127
	v_mov_b32_e32 v111, v127
	v_mov_b32_e32 v110, v127
	v_mov_b32_e32 v109, v127
	v_mov_b32_e32 v108, v127
	v_mov_b32_e32 v107, v127
	v_mov_b32_e32 v106, v127
	v_mov_b32_e32 v105, v127
	v_mov_b32_e32 v104, v127
	v_mov_b32_e32 v95, v127
	v_mov_b32_e32 v94, v127
	v_mov_b32_e32 v93, v127
	v_mov_b32_e32 v92, v127
	v_mov_b32_e32 v91, v127
	v_mov_b32_e32 v90, v127
	v_mov_b32_e32 v89, v127
	v_mov_b32_e32 v88, v127
	v_mov_b32_e32 v79, v127
	v_mov_b32_e32 v78, v127
	v_mov_b32_e32 v77, v127
	v_mov_b32_e32 v76, v127
	v_mov_b32_e32 v75, v127
	v_mov_b32_e32 v74, v127
	v_mov_b32_e32 v73, v127
	v_mov_b32_e32 v72, v127
	v_mov_b32_e32 v119, v127
	v_mov_b32_e32 v118, v127
	v_mov_b32_e32 v117, v127
	v_mov_b32_e32 v116, v127
	v_mov_b32_e32 v115, v127
	v_mov_b32_e32 v114, v127
	v_mov_b32_e32 v113, v127
	v_mov_b32_e32 v112, v127
	v_mov_b32_e32 v103, v127
	v_mov_b32_e32 v102, v127
	v_mov_b32_e32 v101, v127
	v_mov_b32_e32 v100, v127
	v_mov_b32_e32 v99, v127
	v_mov_b32_e32 v98, v127
	v_mov_b32_e32 v97, v127
	v_mov_b32_e32 v96, v127
	v_mov_b32_e32 v87, v127
	v_mov_b32_e32 v86, v127
	v_mov_b32_e32 v85, v127
	v_mov_b32_e32 v84, v127
	v_mov_b32_e32 v83, v127
	v_mov_b32_e32 v82, v127
	v_mov_b32_e32 v81, v127
	v_mov_b32_e32 v80, v127
	v_mov_b32_e32 v71, v127
	v_mov_b32_e32 v70, v127
	v_mov_b32_e32 v69, v127
	v_mov_b32_e32 v68, v127
	v_mov_b32_e32 v67, v127
	v_mov_b32_e32 v66, v127
	v_mov_b32_e32 v65, v127
	v_mov_b32_e32 v64, v127
	v_mov_b32_e32 v63, v127
	v_mov_b32_e32 v62, v127
	v_mov_b32_e32 v61, v127
	v_mov_b32_e32 v60, v127
	v_mov_b32_e32 v59, v127
	v_mov_b32_e32 v58, v127
	v_mov_b32_e32 v57, v127
	v_mov_b32_e32 v56, v127
	v_mov_b32_e32 v47, v127
	v_mov_b32_e32 v46, v127
	v_mov_b32_e32 v45, v127
	v_mov_b32_e32 v44, v127
	v_mov_b32_e32 v43, v127
	v_mov_b32_e32 v42, v127
	v_mov_b32_e32 v41, v127
	v_mov_b32_e32 v40, v127
	v_mov_b32_e32 v31, v127
	v_mov_b32_e32 v30, v127
	v_mov_b32_e32 v29, v127
	v_mov_b32_e32 v28, v127
	v_mov_b32_e32 v27, v127
	v_mov_b32_e32 v26, v127
	v_mov_b32_e32 v25, v127
	v_mov_b32_e32 v24, v127
	v_mov_b32_e32 v15, v127
	v_mov_b32_e32 v14, v127
	v_mov_b32_e32 v13, v127
	v_mov_b32_e32 v12, v127
	v_mov_b32_e32 v11, v127
	v_mov_b32_e32 v10, v127
	v_mov_b32_e32 v9, v127
	v_mov_b32_e32 v8, v127
	v_mov_b32_e32 v55, v127
	v_mov_b32_e32 v54, v127
	v_mov_b32_e32 v53, v127
	v_mov_b32_e32 v52, v127
	v_mov_b32_e32 v51, v127
	v_mov_b32_e32 v50, v127
	v_mov_b32_e32 v49, v127
	v_mov_b32_e32 v48, v127
	v_mov_b32_e32 v39, v127
	v_mov_b32_e32 v38, v127
	v_mov_b32_e32 v37, v127
	v_mov_b32_e32 v36, v127
	v_mov_b32_e32 v35, v127
	v_mov_b32_e32 v34, v127
	v_mov_b32_e32 v33, v127
	v_mov_b32_e32 v32, v127
	v_mov_b32_e32 v23, v127
	v_mov_b32_e32 v22, v127
	v_mov_b32_e32 v21, v127
	v_mov_b32_e32 v20, v127
	v_mov_b32_e32 v19, v127
	v_mov_b32_e32 v18, v127
	v_mov_b32_e32 v17, v127
	v_mov_b32_e32 v16, v127
	v_mov_b32_e32 v7, v127
	v_mov_b32_e32 v6, v127
	v_mov_b32_e32 v5, v127
	v_mov_b32_e32 v4, v127
	s_waitcnt lgkmcnt(0)
	v_mov_b32_e32 v3, v127
	v_mov_b32_e32 v2, v127
	v_mov_b32_e32 v1, v127
	v_mov_b32_e32 v0, v127
	s_cbranch_vccnz .LBB0_900
	s_and_b64 s[42:43], s[6:7], exec
	s_cselect_b32 s27, s31, s41
	s_cselect_b32 s29, s30, s40
	s_cselect_b32 s65, s35, s39
	s_cselect_b32 s66, s34, s38
	s_add_u32 s67, s38, 0x100
	s_addc_u32 s68, s39, 0
	s_add_u32 s38, s40, 0x200080
	v_mov_b32_e32 v0, 0
	s_addc_u32 s39, s41, 0
	s_mov_b32 s40, 0
	v_mov_b32_e32 v1, v0
	v_mov_b32_e32 v2, v0
	v_mov_b32_e32 v3, v0
	v_mov_b32_e32 v4, v0
	v_mov_b32_e32 v5, v0
	v_mov_b32_e32 v6, v0
	v_mov_b32_e32 v7, v0
	v_mov_b32_e32 v16, v0
	v_mov_b32_e32 v17, v0
	v_mov_b32_e32 v18, v0
	v_mov_b32_e32 v19, v0
	v_mov_b32_e32 v20, v0
	v_mov_b32_e32 v21, v0
	v_mov_b32_e32 v22, v0
	v_mov_b32_e32 v23, v0
	v_mov_b32_e32 v32, v0
	v_mov_b32_e32 v33, v0
	v_mov_b32_e32 v34, v0
	v_mov_b32_e32 v35, v0
	v_mov_b32_e32 v36, v0
	v_mov_b32_e32 v37, v0
	v_mov_b32_e32 v38, v0
	v_mov_b32_e32 v39, v0
	v_mov_b32_e32 v48, v0
	v_mov_b32_e32 v49, v0
	v_mov_b32_e32 v50, v0
	v_mov_b32_e32 v51, v0
	v_mov_b32_e32 v52, v0
	v_mov_b32_e32 v53, v0
	v_mov_b32_e32 v54, v0
	v_mov_b32_e32 v55, v0
	v_mov_b32_e32 v8, v0
	v_mov_b32_e32 v9, v0
	v_mov_b32_e32 v10, v0
	v_mov_b32_e32 v11, v0
	v_mov_b32_e32 v12, v0
	v_mov_b32_e32 v13, v0
	v_mov_b32_e32 v14, v0
	v_mov_b32_e32 v15, v0
	v_mov_b32_e32 v24, v0
	v_mov_b32_e32 v25, v0
	v_mov_b32_e32 v26, v0
	v_mov_b32_e32 v27, v0
	v_mov_b32_e32 v28, v0
	v_mov_b32_e32 v29, v0
	v_mov_b32_e32 v30, v0
	v_mov_b32_e32 v31, v0
	v_mov_b32_e32 v40, v0
	v_mov_b32_e32 v41, v0
	v_mov_b32_e32 v42, v0
	v_mov_b32_e32 v43, v0
	v_mov_b32_e32 v44, v0
	v_mov_b32_e32 v45, v0
	v_mov_b32_e32 v46, v0
	v_mov_b32_e32 v47, v0
	v_mov_b32_e32 v56, v0
	v_mov_b32_e32 v57, v0
	v_mov_b32_e32 v58, v0
	v_mov_b32_e32 v59, v0
	v_mov_b32_e32 v60, v0
	v_mov_b32_e32 v61, v0
	v_mov_b32_e32 v62, v0
	v_mov_b32_e32 v63, v0
	v_mov_b32_e32 v64, v0
	v_mov_b32_e32 v65, v0
	v_mov_b32_e32 v66, v0
	v_mov_b32_e32 v67, v0
	v_mov_b32_e32 v68, v0
	v_mov_b32_e32 v69, v0
	v_mov_b32_e32 v70, v0
	v_mov_b32_e32 v71, v0
	v_mov_b32_e32 v80, v0
	v_mov_b32_e32 v81, v0
	v_mov_b32_e32 v82, v0
	v_mov_b32_e32 v83, v0
	v_mov_b32_e32 v84, v0
	v_mov_b32_e32 v85, v0
	v_mov_b32_e32 v86, v0
	v_mov_b32_e32 v87, v0
	v_mov_b32_e32 v96, v0
	v_mov_b32_e32 v97, v0
	v_mov_b32_e32 v98, v0
	v_mov_b32_e32 v99, v0
	v_mov_b32_e32 v100, v0
	v_mov_b32_e32 v101, v0
	v_mov_b32_e32 v102, v0
	v_mov_b32_e32 v103, v0
	v_mov_b32_e32 v112, v0
	v_mov_b32_e32 v113, v0
	v_mov_b32_e32 v114, v0
	v_mov_b32_e32 v115, v0
	v_mov_b32_e32 v116, v0
	v_mov_b32_e32 v117, v0
	v_mov_b32_e32 v118, v0
	v_mov_b32_e32 v119, v0
	v_mov_b32_e32 v72, v0
	v_mov_b32_e32 v73, v0
	v_mov_b32_e32 v74, v0
	v_mov_b32_e32 v75, v0
	v_mov_b32_e32 v76, v0
	v_mov_b32_e32 v77, v0
	v_mov_b32_e32 v78, v0
	v_mov_b32_e32 v79, v0
	v_mov_b32_e32 v88, v0
	v_mov_b32_e32 v89, v0
	v_mov_b32_e32 v90, v0
	v_mov_b32_e32 v91, v0
	v_mov_b32_e32 v92, v0
	v_mov_b32_e32 v93, v0
	v_mov_b32_e32 v94, v0
	v_mov_b32_e32 v95, v0
	v_mov_b32_e32 v104, v0
	v_mov_b32_e32 v105, v0
	v_mov_b32_e32 v106, v0
	v_mov_b32_e32 v107, v0
	v_mov_b32_e32 v108, v0
	v_mov_b32_e32 v109, v0
	v_mov_b32_e32 v110, v0
	v_mov_b32_e32 v111, v0
	v_mov_b32_e32 v120, v0
	v_mov_b32_e32 v121, v0
	v_mov_b32_e32 v122, v0
	v_mov_b32_e32 v123, v0
	v_mov_b32_e32 v124, v0
	v_mov_b32_e32 v125, v0
	v_mov_b32_e32 v126, v0
	v_mov_b32_e32 v127, v0
	.p2align	6

;     __host__ __device__ bool next(int i, Unit& u) const { return i < cnt ? so.next(base + i, u) : false; }
;     __host__ __device__ bool next(int i, Unit& u) const { const int L = i * G + c; if (L >= 32) return false; u.g = L >> 3; u.pm = L & 7; u.pn = 0; return true; }
;   __device__ __forceinline__ bool next(int i,AttnUnit&u)const{ if(i>=4)return false; const int s=vcu&7; u.bh=vcu>>3; u.qb=(i==0)?s:(i==1)?15-s:(i==2)?16+s:31-s; return true; }
; template <class Epi, class Sched, bool ALIGN_EPI = false, bool SP2 = false>
; __device__ __forceinline__ void gemm_phase(PG8_LAS unsigned char* lds, const Gemm g, const Sched& S, const Epi& E) {
;     ...
;         const bool has_next = S.next(ui + 1, nxt);
;         const char* nA = has_next ? (const char*)(g.A + (size_t)nxt.g * g.gsA) + (size_t)nxt.pm * tstepA : cA; const char* nB = has_next ? (const char*)(g.Bt + (size_t)nxt.g * g.gsB) + (size_t)nxt.pn * tstepB : cB;
;         for (int t = 0; t < nt; t += 2) {
;             if constexpr (Epi::MIDK) { if (t == (nt >> 1)) { asm volatile("s_waitcnt vmcnt(0)" ::: "memory"); E.mid(acc, cur, wr, wc, fr, fq); asm volatile("s_waitcnt vmcnt(0)" ::: "memory"); } }
;             const bool last = (t == nt - 2);
;             const char* a1 = cA + (size_t)(t + 1) * kstep;
;             const char* a2 = last ? nA : cA + (size_t)(t + 2) * kstep; const char* b2 = last ? nB : cB + (size_t)(t + 2) * kstep;
;             const char* a3 = a2 + kstep; const char* b3 = b2 + kstep;
;     ...
; #pragma unroll
;         for (int a = 0; a < 2; ++a)
; #pragma unroll
;             for (int b = 0; b < 2; ++b)
; #pragma unroll
;                 for (int m = 0; m < 4; ++m)
; #pragma unroll
;                     for (int n = 0; n < 2; ++n) acc[a][b][m][n] = (f32x4){0.f, 0.f, 0.f, 0.f};
.LBB0_986:
	s_ashr_i32 s35, s34, 31
	s_lshl_b64 s[36:37], s[34:35], 17
	s_add_u32 s36, s48, s36
	s_addc_u32 s37, s49, s37
	s_ashr_i32 s31, s30, 31
	s_lshl_b64 s[38:39], s[30:31], 17
	s_add_u32 s38, s50, s38
	v_mov_b32_e32 v127, 0
	s_addc_u32 s39, s51, s39
	s_and_b64 vcc, exec, s[6:7]
	v_mov_b32_e32 v126, v127
	v_mov_b32_e32 v125, v127
	v_mov_b32_e32 v124, v127
	v_mov_b32_e32 v123, v127
	v_mov_b32_e32 v122, v127
	v_mov_b32_e32 v121, v127
	v_mov_b32_e32 v120, v127
	v_mov_b32_e32 v111, v127
	v_mov_b32_e32 v110, v127
	v_mov_b32_e32 v109, v127
	v_mov_b32_e32 v108, v127
	v_mov_b32_e32 v107, v127
	v_mov_b32_e32 v106, v127
	v_mov_b32_e32 v105, v127
	v_mov_b32_e32 v104, v127
	v_mov_b32_e32 v95, v127
	v_mov_b32_e32 v94, v127
	v_mov_b32_e32 v93, v127
	v_mov_b32_e32 v92, v127
	v_mov_b32_e32 v91, v127
	v_mov_b32_e32 v90, v127
	v_mov_b32_e32 v89, v127
	v_mov_b32_e32 v88, v127
	v_mov_b32_e32 v79, v127
	v_mov_b32_e32 v78, v127
	v_mov_b32_e32 v77, v127
	v_mov_b32_e32 v76, v127
	v_mov_b32_e32 v75, v127
	v_mov_b32_e32 v74, v127
	v_mov_b32_e32 v73, v127
	v_mov_b32_e32 v72, v127
	v_mov_b32_e32 v119, v127
	v_mov_b32_e32 v118, v127
	v_mov_b32_e32 v117, v127
	v_mov_b32_e32 v116, v127
	v_mov_b32_e32 v115, v127
	v_mov_b32_e32 v114, v127
	v_mov_b32_e32 v113, v127
	v_mov_b32_e32 v112, v127
	v_mov_b32_e32 v103, v127
	v_mov_b32_e32 v102, v127
	v_mov_b32_e32 v101, v127
	v_mov_b32_e32 v100, v127
	v_mov_b32_e32 v99, v127
	v_mov_b32_e32 v98, v127
	v_mov_b32_e32 v97, v127
	v_mov_b32_e32 v96, v127
	v_mov_b32_e32 v87, v127
	v_mov_b32_e32 v86, v127
	v_mov_b32_e32 v85, v127
	v_mov_b32_e32 v84, v127
	v_mov_b32_e32 v83, v127
	v_mov_b32_e32 v82, v127
	v_mov_b32_e32 v81, v127
	v_mov_b32_e32 v80, v127
	v_mov_b32_e32 v71, v127
	v_mov_b32_e32 v70, v127
	v_mov_b32_e32 v69, v127
	v_mov_b32_e32 v68, v127
	v_mov_b32_e32 v67, v127
	v_mov_b32_e32 v66, v127
	v_mov_b32_e32 v65, v127
	v_mov_b32_e32 v64, v127
	v_mov_b32_e32 v63, v127
	v_mov_b32_e32 v62, v127
	v_mov_b32_e32 v61, v127
	v_mov_b32_e32 v60, v127
	v_mov_b32_e32 v59, v127
	v_mov_b32_e32 v58, v127
	v_mov_b32_e32 v57, v127
	v_mov_b32_e32 v56, v127
	v_mov_b32_e32 v47, v127
	v_mov_b32_e32 v46, v127
	v_mov_b32_e32 v45, v127
	v_mov_b32_e32 v44, v127
	v_mov_b32_e32 v43, v127
	v_mov_b32_e32 v42, v127
	v_mov_b32_e32 v41, v127
	v_mov_b32_e32 v40, v127
	v_mov_b32_e32 v31, v127
	v_mov_b32_e32 v30, v127
	v_mov_b32_e32 v29, v127
	v_mov_b32_e32 v28, v127
	v_mov_b32_e32 v27, v127
	v_mov_b32_e32 v26, v127
	v_mov_b32_e32 v25, v127
	v_mov_b32_e32 v24, v127
	v_mov_b32_e32 v15, v127
	v_mov_b32_e32 v14, v127
	v_mov_b32_e32 v13, v127
	v_mov_b32_e32 v12, v127
	v_mov_b32_e32 v11, v127
	v_mov_b32_e32 v10, v127
	v_mov_b32_e32 v9, v127
	v_mov_b32_e32 v8, v127
	v_mov_b32_e32 v55, v127
	v_mov_b32_e32 v54, v127
	v_mov_b32_e32 v53, v127
	v_mov_b32_e32 v52, v127
	v_mov_b32_e32 v51, v127
	v_mov_b32_e32 v50, v127
	v_mov_b32_e32 v49, v127
	v_mov_b32_e32 v48, v127
	v_mov_b32_e32 v39, v127
	v_mov_b32_e32 v38, v127
	v_mov_b32_e32 v37, v127
	v_mov_b32_e32 v36, v127
	v_mov_b32_e32 v35, v127
	v_mov_b32_e32 v34, v127
	v_mov_b32_e32 v33, v127
	v_mov_b32_e32 v32, v127
	v_mov_b32_e32 v23, v127
	v_mov_b32_e32 v22, v127
	v_mov_b32_e32 v21, v127
	v_mov_b32_e32 v20, v127
	v_mov_b32_e32 v19, v127
	v_mov_b32_e32 v18, v127
	v_mov_b32_e32 v17, v127
	v_mov_b32_e32 v16, v127
	v_mov_b32_e32 v7, v127
	v_mov_b32_e32 v6, v127
	v_mov_b32_e32 v5, v127
	v_mov_b32_e32 v4, v127
	v_mov_b32_e32 v3, v127
	v_mov_b32_e32 v2, v127
	v_mov_b32_e32 v1, v127
	v_mov_b32_e32 v0, v127
	s_cbranch_vccnz .LBB0_989
	s_and_b64 s[44:45], s[8:9], exec
	s_cselect_b32 s31, s37, s43
	s_cselect_b32 s35, s36, s42
	s_cselect_b32 s67, s39, s41
	s_cselect_b32 s68, s38, s40
	s_add_u32 s69, s40, 0x100
	s_addc_u32 s70, s41, 0
	s_add_u32 s40, s42, 0x10080
	v_mov_b32_e32 v0, 0
	s_addc_u32 s41, s43, 0
	s_mov_b32 s42, 0
	v_mov_b32_e32 v1, v0
	v_mov_b32_e32 v2, v0
	v_mov_b32_e32 v3, v0
	v_mov_b32_e32 v4, v0
	v_mov_b32_e32 v5, v0
	v_mov_b32_e32 v6, v0
	v_mov_b32_e32 v7, v0
	v_mov_b32_e32 v16, v0
	v_mov_b32_e32 v17, v0
	v_mov_b32_e32 v18, v0
	v_mov_b32_e32 v19, v0
	v_mov_b32_e32 v20, v0
	v_mov_b32_e32 v21, v0
	v_mov_b32_e32 v22, v0
	v_mov_b32_e32 v23, v0
	v_mov_b32_e32 v32, v0
	v_mov_b32_e32 v33, v0
	v_mov_b32_e32 v34, v0
	v_mov_b32_e32 v35, v0
	v_mov_b32_e32 v36, v0
	v_mov_b32_e32 v37, v0
	v_mov_b32_e32 v38, v0
	v_mov_b32_e32 v39, v0
	v_mov_b32_e32 v48, v0
	v_mov_b32_e32 v49, v0
	v_mov_b32_e32 v50, v0
	v_mov_b32_e32 v51, v0
	v_mov_b32_e32 v52, v0
	v_mov_b32_e32 v53, v0
	v_mov_b32_e32 v54, v0
	v_mov_b32_e32 v55, v0
	v_mov_b32_e32 v8, v0
	v_mov_b32_e32 v9, v0
	v_mov_b32_e32 v10, v0
	v_mov_b32_e32 v11, v0
	v_mov_b32_e32 v12, v0
	v_mov_b32_e32 v13, v0
	v_mov_b32_e32 v14, v0
	v_mov_b32_e32 v15, v0
	v_mov_b32_e32 v24, v0
	v_mov_b32_e32 v25, v0
	v_mov_b32_e32 v26, v0
	v_mov_b32_e32 v27, v0
	v_mov_b32_e32 v28, v0
	v_mov_b32_e32 v29, v0
	v_mov_b32_e32 v30, v0
	v_mov_b32_e32 v31, v0
	v_mov_b32_e32 v40, v0
	v_mov_b32_e32 v41, v0
	v_mov_b32_e32 v42, v0
	v_mov_b32_e32 v43, v0
	v_mov_b32_e32 v44, v0
	v_mov_b32_e32 v45, v0
	v_mov_b32_e32 v46, v0
	v_mov_b32_e32 v47, v0
	v_mov_b32_e32 v56, v0
	v_mov_b32_e32 v57, v0
	v_mov_b32_e32 v58, v0
	v_mov_b32_e32 v59, v0
	v_mov_b32_e32 v60, v0
	v_mov_b32_e32 v61, v0
	v_mov_b32_e32 v62, v0
	v_mov_b32_e32 v63, v0
	v_mov_b32_e32 v64, v0
	v_mov_b32_e32 v65, v0
	v_mov_b32_e32 v66, v0
	v_mov_b32_e32 v67, v0
	v_mov_b32_e32 v68, v0
	v_mov_b32_e32 v69, v0
	v_mov_b32_e32 v70, v0
	v_mov_b32_e32 v71, v0
	v_mov_b32_e32 v80, v0
	v_mov_b32_e32 v81, v0
	v_mov_b32_e32 v82, v0
	v_mov_b32_e32 v83, v0
	v_mov_b32_e32 v84, v0
	v_mov_b32_e32 v85, v0
	v_mov_b32_e32 v86, v0
	v_mov_b32_e32 v87, v0
	v_mov_b32_e32 v96, v0
	v_mov_b32_e32 v97, v0
	v_mov_b32_e32 v98, v0
	v_mov_b32_e32 v99, v0
	v_mov_b32_e32 v100, v0
	v_mov_b32_e32 v101, v0
	v_mov_b32_e32 v102, v0
	v_mov_b32_e32 v103, v0
	v_mov_b32_e32 v112, v0
	v_mov_b32_e32 v113, v0
	v_mov_b32_e32 v114, v0
	v_mov_b32_e32 v115, v0
	v_mov_b32_e32 v116, v0
	v_mov_b32_e32 v117, v0
	v_mov_b32_e32 v118, v0
	v_mov_b32_e32 v119, v0
	v_mov_b32_e32 v72, v0
	v_mov_b32_e32 v73, v0
	v_mov_b32_e32 v74, v0
	v_mov_b32_e32 v75, v0
	v_mov_b32_e32 v76, v0
	v_mov_b32_e32 v77, v0
	v_mov_b32_e32 v78, v0
	v_mov_b32_e32 v79, v0
	v_mov_b32_e32 v88, v0
	v_mov_b32_e32 v89, v0
	v_mov_b32_e32 v90, v0
	v_mov_b32_e32 v91, v0
	v_mov_b32_e32 v92, v0
	v_mov_b32_e32 v93, v0
	v_mov_b32_e32 v94, v0
	v_mov_b32_e32 v95, v0
	v_mov_b32_e32 v104, v0
	v_mov_b32_e32 v105, v0
	v_mov_b32_e32 v106, v0
	v_mov_b32_e32 v107, v0
	v_mov_b32_e32 v108, v0
	v_mov_b32_e32 v109, v0
	v_mov_b32_e32 v110, v0
	v_mov_b32_e32 v111, v0
	v_mov_b32_e32 v120, v0
	v_mov_b32_e32 v121, v0
	v_mov_b32_e32 v122, v0
	v_mov_b32_e32 v123, v0
	v_mov_b32_e32 v124, v0
	v_mov_b32_e32 v125, v0
	v_mov_b32_e32 v126, v0
	v_mov_b32_e32 v127, v0
	.p2align	6

;     __host__ __device__ bool next(int i, Unit& u) const { return i < cnt ? so.next(base + i, u) : false; }
;     __host__ __device__ bool next(int i, Unit& u) const { const int L = i * G + c; if (L >= 32) return false; u.g = L >> 3; u.pm = L & 7; u.pn = 0; return true; }
;   __device__ __forceinline__ bool next(int i,AttnUnit&u)const{ if(i>=4)return false; const int s=vcu&7; u.bh=vcu>>3; u.qb=(i==0)?s:(i==1)?15-s:(i==2)?16+s:31-s; return true; }
; template <class Epi, class Sched, bool ALIGN_EPI = false, bool SP2 = false>
; __device__ __forceinline__ void gemm_phase(PG8_LAS unsigned char* lds, const Gemm g, const Sched& S, const Epi& E) {
;     ...
;         const bool has_next = S.next(ui + 1, nxt);
;         const char* nA = has_next ? (const char*)(g.A + (size_t)nxt.g * g.gsA) + (size_t)nxt.pm * tstepA : cA; const char* nB = has_next ? (const char*)(g.Bt + (size_t)nxt.g * g.gsB) + (size_t)nxt.pn * tstepB : cB;
;         for (int t = 0; t < nt; t += 2) {
;             if constexpr (Epi::MIDK) { if (t == (nt >> 1)) { asm volatile("s_waitcnt vmcnt(0)" ::: "memory"); E.mid(acc, cur, wr, wc, fr, fq); asm volatile("s_waitcnt vmcnt(0)" ::: "memory"); } }
;             const bool last = (t == nt - 2);
;             const char* a1 = cA + (size_t)(t + 1) * kstep;
;             const char* a2 = last ? nA : cA + (size_t)(t + 2) * kstep; const char* b2 = last ? nB : cB + (size_t)(t + 2) * kstep;
;             const char* a3 = a2 + kstep; const char* b3 = b2 + kstep;
.LBB0_1012:
	s_ashr_i32 s29, s28, 31
	s_lshl_b64 s[30:31], s[28:29], 20
	s_add_u32 s30, s16, s30
	s_addc_u32 s31, s17, s31
	s_ashr_i32 s27, s26, 31
	s_lshl_b64 s[34:35], s[26:27], 20
	s_add_u32 s34, s44, s34
	s_addc_u32 s35, s45, s35
	s_andn2_b64 vcc, exec, s[24:25]
	s_cbranch_vccnz .LBB0_1015
	s_and_b64 s[36:37], s[6:7], exec
	s_cselect_b32 s27, s31, s21
	s_cselect_b32 s29, s30, s20
	s_cselect_b32 s62, s35, s19
	s_cselect_b32 s63, s34, s18
	s_add_u32 s64, s18, 0x100
	s_addc_u32 s65, s19, 0
	s_add_u32 s36, s20, 0x80080
	s_addc_u32 s37, s21, 0
	s_mov_b32 s38, 0
	.p2align	6
